# EPI-1 epilogue rewritten (LDS-staged, 16B RMW) + software-pipelined RWKV scan inner loop
# speedup vs baseline: 1.0388x; 1.0388x over previous
.LBB0_555:
	s_nop 1
	v_cndmask_b32_e64 v63, 0, 1, s[34:35]
	s_movk_i32 s16, 0x5800
	v_mul_lo_u32 v64, v63, s16
	v_add_u32_e32 v62, v60, v64
	v_lshl_add_u32 v63, v63, 12, v61
	v_or_b32_e32 v64, v24, v64
	s_mov_b32 s16, 0
	ds_read_u16 v182, v62
	ds_read_b128 v[162:165], v64
	ds_read_b128 v[166:169], v64 offset:128
	ds_read_b128 v[170:173], v64 offset:256
	ds_read_b128 v[174:177], v64 offset:384
	ds_read_b128 v[178:181], v64 offset:512
	s_branch .LBB0_557

.LBB0_557:
	v_add_u32_e32 v65, s16, v62
	ds_read_u16 v204, v65 offset:64
	ds_read_b128 v[184:187], v64 offset:640
	ds_read_b128 v[188:191], v64 offset:768
	ds_read_b128 v[192:195], v64 offset:896
	ds_read_b128 v[196:199], v64 offset:1024
	ds_read_b128 v[200:203], v64 offset:1152
	s_waitcnt lgkmcnt(6)
	v_lshlrev_b32_e32 v206, 16, v166
	v_lshlrev_b32_e32 v207, 16, v167
	v_lshlrev_b32_e32 v208, 16, v168
	v_lshlrev_b32_e32 v209, 16, v169
	v_pk_mul_f32 v[228:229], v[44:45], v[206:207]
	v_pk_mul_f32 v[230:231], v[46:47], v[208:209]
	v_pk_fma_f32 v[228:229], v[40:41], v[166:167], v[228:229]
	v_pk_fma_f32 v[230:231], v[42:43], v[168:169], v[230:231]
	v_lshlrev_b32_e32 v210, 16, v170
	v_pk_add_f32 v[228:229], v[228:229], v[230:231]
	v_lshlrev_b32_e32 v211, 16, v171
	v_add_f32_e32 v232, v228, v229
	v_lshlrev_b32_e32 v212, 16, v172
	v_lshlrev_b32_e32 v213, 16, v173
	v_add_f32_dpp v232, v232, v232 quad_perm:[1,0,3,2] row_mask:0xf bank_mask:0xf bound_ctrl:1
	v_pk_fma_f32 v[234:235], v[40:41], v[170:171], v[40:41] neg_lo:[1,0,0] neg_hi:[1,0,0]
	v_pk_fma_f32 v[236:237], v[42:43], v[172:173], v[42:43] neg_lo:[1,0,0] neg_hi:[1,0,0]
	v_add_f32_dpp v232, v232, v232 quad_perm:[2,3,0,1] row_mask:0xf bank_mask:0xf bound_ctrl:1
	v_pk_fma_f32 v[238:239], v[44:45], v[210:211], v[44:45] neg_lo:[1,0,0] neg_hi:[1,0,0]
	v_pk_fma_f32 v[240:241], v[46:47], v[212:213], v[46:47] neg_lo:[1,0,0] neg_hi:[1,0,0]
	v_add_f32_dpp v232, v232, v232 row_half_mirror row_mask:0xf bank_mask:0xf bound_ctrl:1
	v_lshlrev_b32_e32 v226, 16, v182
	v_lshlrev_b32_e32 v214, 16, v174
	v_lshlrev_b32_e32 v215, 16, v175
	v_lshlrev_b32_e32 v216, 16, v176
	v_lshlrev_b32_e32 v217, 16, v177
	v_pk_fma_f32 v[234:235], v[226:227], v[174:175], v[234:235] op_sel_hi:[0,1,1]
	v_pk_fma_f32 v[236:237], v[226:227], v[176:177], v[236:237] op_sel_hi:[0,1,1]
	v_pk_fma_f32 v[238:239], v[226:227], v[214:215], v[238:239] op_sel_hi:[0,1,1]
	v_pk_fma_f32 v[240:241], v[226:227], v[216:217], v[240:241] op_sel_hi:[0,1,1]
	v_lshlrev_b32_e32 v218, 16, v178
	v_lshlrev_b32_e32 v219, 16, v179
	v_lshlrev_b32_e32 v220, 16, v180
	v_lshlrev_b32_e32 v221, 16, v181
	v_pk_fma_f32 v[40:41], v[232:233], v[178:179], v[234:235] op_sel_hi:[0,1,1] neg_lo:[1,0,0] neg_hi:[1,0,0]
	v_pk_fma_f32 v[42:43], v[232:233], v[180:181], v[236:237] op_sel_hi:[0,1,1] neg_lo:[1,0,0] neg_hi:[1,0,0]
	v_pk_fma_f32 v[44:45], v[232:233], v[218:219], v[238:239] op_sel_hi:[0,1,1] neg_lo:[1,0,0] neg_hi:[1,0,0]
	v_pk_fma_f32 v[46:47], v[232:233], v[220:221], v[240:241] op_sel_hi:[0,1,1] neg_lo:[1,0,0] neg_hi:[1,0,0]
	v_lshlrev_b32_e32 v222, 16, v162
	v_lshlrev_b32_e32 v223, 16, v163
	v_lshlrev_b32_e32 v224, 16, v164
	v_lshlrev_b32_e32 v225, 16, v165
	v_pk_mul_f32 v[242:243], v[40:41], v[162:163]
	v_pk_mul_f32 v[244:245], v[42:43], v[164:165]
	v_pk_fma_f32 v[242:243], v[44:45], v[222:223], v[242:243]
	v_pk_fma_f32 v[244:245], v[46:47], v[224:225], v[244:245]
	ds_read_u16 v182, v65 offset:128
	ds_read_b128 v[162:165], v64 offset:1280
	ds_read_b128 v[166:169], v64 offset:1408
	ds_read_b128 v[170:173], v64 offset:1536
	ds_read_b128 v[174:177], v64 offset:1664
	ds_read_b128 v[178:181], v64 offset:1792
	v_pk_add_f32 v[242:243], v[242:243], v[244:245]
	s_waitcnt lgkmcnt(6)
	v_lshlrev_b32_e32 v206, 16, v188
	v_add_f32_e32 v246, v242, v243
	v_lshlrev_b32_e32 v207, 16, v189
	v_lshlrev_b32_e32 v208, 16, v190
	v_add_f32_dpp v246, v246, v246 quad_perm:[1,0,3,2] row_mask:0xf bank_mask:0xf bound_ctrl:1
	v_lshlrev_b32_e32 v209, 16, v191
	v_pk_mul_f32 v[228:229], v[44:45], v[206:207]
	v_add_f32_dpp v246, v246, v246 quad_perm:[2,3,0,1] row_mask:0xf bank_mask:0xf bound_ctrl:1
	v_pk_mul_f32 v[230:231], v[46:47], v[208:209]
	v_pk_fma_f32 v[228:229], v[40:41], v[188:189], v[228:229]
	v_add_f32_dpp v246, v246, v246 row_half_mirror row_mask:0xf bank_mask:0xf bound_ctrl:1
	v_pk_fma_f32 v[230:231], v[42:43], v[190:191], v[230:231]
	s_and_saveexec_b64 s[50:51], s[8:9]
	ds_write_b32 v63, v246
	s_or_b64 exec, exec, s[50:51]
	v_pk_add_f32 v[228:229], v[228:229], v[230:231]
	v_lshlrev_b32_e32 v210, 16, v192
	v_lshlrev_b32_e32 v211, 16, v193
	v_add_f32_e32 v232, v228, v229
	v_lshlrev_b32_e32 v212, 16, v194
	v_lshlrev_b32_e32 v213, 16, v195
	v_add_f32_dpp v232, v232, v232 quad_perm:[1,0,3,2] row_mask:0xf bank_mask:0xf bound_ctrl:1
	v_pk_fma_f32 v[234:235], v[40:41], v[192:193], v[40:41] neg_lo:[1,0,0] neg_hi:[1,0,0]
	v_pk_fma_f32 v[236:237], v[42:43], v[194:195], v[42:43] neg_lo:[1,0,0] neg_hi:[1,0,0]
	v_add_f32_dpp v232, v232, v232 quad_perm:[2,3,0,1] row_mask:0xf bank_mask:0xf bound_ctrl:1
	v_pk_fma_f32 v[238:239], v[44:45], v[210:211], v[44:45] neg_lo:[1,0,0] neg_hi:[1,0,0]
	v_pk_fma_f32 v[240:241], v[46:47], v[212:213], v[46:47] neg_lo:[1,0,0] neg_hi:[1,0,0]
	v_add_f32_dpp v232, v232, v232 row_half_mirror row_mask:0xf bank_mask:0xf bound_ctrl:1
	v_lshlrev_b32_e32 v226, 16, v204
	v_lshlrev_b32_e32 v214, 16, v196
	v_lshlrev_b32_e32 v215, 16, v197
	v_lshlrev_b32_e32 v216, 16, v198
	v_lshlrev_b32_e32 v217, 16, v199
	v_pk_fma_f32 v[234:235], v[226:227], v[196:197], v[234:235] op_sel_hi:[0,1,1]
	v_pk_fma_f32 v[236:237], v[226:227], v[198:199], v[236:237] op_sel_hi:[0,1,1]
	v_pk_fma_f32 v[238:239], v[226:227], v[214:215], v[238:239] op_sel_hi:[0,1,1]
	v_pk_fma_f32 v[240:241], v[226:227], v[216:217], v[240:241] op_sel_hi:[0,1,1]
	v_lshlrev_b32_e32 v218, 16, v200
	v_lshlrev_b32_e32 v219, 16, v201
	v_lshlrev_b32_e32 v220, 16, v202
	v_lshlrev_b32_e32 v221, 16, v203
	v_pk_fma_f32 v[40:41], v[232:233], v[200:201], v[234:235] op_sel_hi:[0,1,1] neg_lo:[1,0,0] neg_hi:[1,0,0]
	v_pk_fma_f32 v[42:43], v[232:233], v[202:203], v[236:237] op_sel_hi:[0,1,1] neg_lo:[1,0,0] neg_hi:[1,0,0]
	v_pk_fma_f32 v[44:45], v[232:233], v[218:219], v[238:239] op_sel_hi:[0,1,1] neg_lo:[1,0,0] neg_hi:[1,0,0]
	v_pk_fma_f32 v[46:47], v[232:233], v[220:221], v[240:241] op_sel_hi:[0,1,1] neg_lo:[1,0,0] neg_hi:[1,0,0]
	v_lshlrev_b32_e32 v222, 16, v184
	v_lshlrev_b32_e32 v223, 16, v185
	v_lshlrev_b32_e32 v224, 16, v186
	v_lshlrev_b32_e32 v225, 16, v187
	v_pk_mul_f32 v[242:243], v[40:41], v[184:185]
	v_pk_mul_f32 v[244:245], v[42:43], v[186:187]
	v_pk_fma_f32 v[242:243], v[44:45], v[222:223], v[242:243]
	v_pk_fma_f32 v[244:245], v[46:47], v[224:225], v[244:245]
	ds_read_u16 v204, v65 offset:192
	ds_read_b128 v[184:187], v64 offset:1920
	ds_read_b128 v[188:191], v64 offset:2048
	ds_read_b128 v[192:195], v64 offset:2176
	ds_read_b128 v[196:199], v64 offset:2304
	ds_read_b128 v[200:203], v64 offset:2432
	v_pk_add_f32 v[242:243], v[242:243], v[244:245]
	s_waitcnt lgkmcnt(6)
	v_lshlrev_b32_e32 v206, 16, v166
	v_add_f32_e32 v248, v242, v243
	v_lshlrev_b32_e32 v207, 16, v167
	v_lshlrev_b32_e32 v208, 16, v168
	v_add_f32_dpp v248, v248, v248 quad_perm:[1,0,3,2] row_mask:0xf bank_mask:0xf bound_ctrl:1
	v_lshlrev_b32_e32 v209, 16, v169
	v_pk_mul_f32 v[228:229], v[44:45], v[206:207]
	v_add_f32_dpp v248, v248, v248 quad_perm:[2,3,0,1] row_mask:0xf bank_mask:0xf bound_ctrl:1
	v_pk_mul_f32 v[230:231], v[46:47], v[208:209]
	v_pk_fma_f32 v[228:229], v[40:41], v[166:167], v[228:229]
	v_add_f32_dpp v248, v248, v248 row_half_mirror row_mask:0xf bank_mask:0xf bound_ctrl:1
	v_pk_fma_f32 v[230:231], v[42:43], v[168:169], v[230:231]
	s_and_saveexec_b64 s[50:51], s[8:9]
	ds_write_b32 v63, v248 offset:128
	s_or_b64 exec, exec, s[50:51]
	v_pk_add_f32 v[228:229], v[228:229], v[230:231]
	v_lshlrev_b32_e32 v210, 16, v170
	v_lshlrev_b32_e32 v211, 16, v171
	v_add_f32_e32 v232, v228, v229
	v_lshlrev_b32_e32 v212, 16, v172
	v_lshlrev_b32_e32 v213, 16, v173
	v_add_f32_dpp v232, v232, v232 quad_perm:[1,0,3,2] row_mask:0xf bank_mask:0xf bound_ctrl:1
	v_pk_fma_f32 v[234:235], v[40:41], v[170:171], v[40:41] neg_lo:[1,0,0] neg_hi:[1,0,0]
	v_pk_fma_f32 v[236:237], v[42:43], v[172:173], v[42:43] neg_lo:[1,0,0] neg_hi:[1,0,0]
	v_add_f32_dpp v232, v232, v232 quad_perm:[2,3,0,1] row_mask:0xf bank_mask:0xf bound_ctrl:1
	v_pk_fma_f32 v[238:239], v[44:45], v[210:211], v[44:45] neg_lo:[1,0,0] neg_hi:[1,0,0]
	v_pk_fma_f32 v[240:241], v[46:47], v[212:213], v[46:47] neg_lo:[1,0,0] neg_hi:[1,0,0]
	v_add_f32_dpp v232, v232, v232 row_half_mirror row_mask:0xf bank_mask:0xf bound_ctrl:1
	v_lshlrev_b32_e32 v226, 16, v182
	v_lshlrev_b32_e32 v214, 16, v174
	v_lshlrev_b32_e32 v215, 16, v175
	v_lshlrev_b32_e32 v216, 16, v176
	v_lshlrev_b32_e32 v217, 16, v177
	v_pk_fma_f32 v[234:235], v[226:227], v[174:175], v[234:235] op_sel_hi:[0,1,1]
	v_pk_fma_f32 v[236:237], v[226:227], v[176:177], v[236:237] op_sel_hi:[0,1,1]
	v_pk_fma_f32 v[238:239], v[226:227], v[214:215], v[238:239] op_sel_hi:[0,1,1]
	v_pk_fma_f32 v[240:241], v[226:227], v[216:217], v[240:241] op_sel_hi:[0,1,1]
	v_lshlrev_b32_e32 v218, 16, v178
	v_lshlrev_b32_e32 v219, 16, v179
	v_lshlrev_b32_e32 v220, 16, v180
	v_lshlrev_b32_e32 v221, 16, v181
	v_pk_fma_f32 v[40:41], v[232:233], v[178:179], v[234:235] op_sel_hi:[0,1,1] neg_lo:[1,0,0] neg_hi:[1,0,0]
	v_pk_fma_f32 v[42:43], v[232:233], v[180:181], v[236:237] op_sel_hi:[0,1,1] neg_lo:[1,0,0] neg_hi:[1,0,0]
	v_pk_fma_f32 v[44:45], v[232:233], v[218:219], v[238:239] op_sel_hi:[0,1,1] neg_lo:[1,0,0] neg_hi:[1,0,0]
	v_pk_fma_f32 v[46:47], v[232:233], v[220:221], v[240:241] op_sel_hi:[0,1,1] neg_lo:[1,0,0] neg_hi:[1,0,0]
	v_lshlrev_b32_e32 v222, 16, v162
	v_lshlrev_b32_e32 v223, 16, v163
	v_lshlrev_b32_e32 v224, 16, v164
	v_lshlrev_b32_e32 v225, 16, v165
	v_pk_mul_f32 v[242:243], v[40:41], v[162:163]
	v_pk_mul_f32 v[244:245], v[42:43], v[164:165]
	v_pk_fma_f32 v[242:243], v[44:45], v[222:223], v[242:243]
	v_pk_fma_f32 v[244:245], v[46:47], v[224:225], v[244:245]
	ds_read_u16 v182, v65 offset:256
	ds_read_b128 v[162:165], v64 offset:2560
	ds_read_b128 v[166:169], v64 offset:2688
	ds_read_b128 v[170:173], v64 offset:2816
	ds_read_b128 v[174:177], v64 offset:2944
	ds_read_b128 v[178:181], v64 offset:3072
	v_pk_add_f32 v[242:243], v[242:243], v[244:245]
	s_waitcnt lgkmcnt(6)
	v_lshlrev_b32_e32 v206, 16, v188
	v_add_f32_e32 v246, v242, v243
	v_lshlrev_b32_e32 v207, 16, v189
	v_lshlrev_b32_e32 v208, 16, v190
	v_add_f32_dpp v246, v246, v246 quad_perm:[1,0,3,2] row_mask:0xf bank_mask:0xf bound_ctrl:1
	v_lshlrev_b32_e32 v209, 16, v191
	v_pk_mul_f32 v[228:229], v[44:45], v[206:207]
	v_add_f32_dpp v246, v246, v246 quad_perm:[2,3,0,1] row_mask:0xf bank_mask:0xf bound_ctrl:1
	v_pk_mul_f32 v[230:231], v[46:47], v[208:209]
	v_pk_fma_f32 v[228:229], v[40:41], v[188:189], v[228:229]
	v_add_f32_dpp v246, v246, v246 row_half_mirror row_mask:0xf bank_mask:0xf bound_ctrl:1
	v_pk_fma_f32 v[230:231], v[42:43], v[190:191], v[230:231]
	s_and_saveexec_b64 s[50:51], s[8:9]
	ds_write_b32 v63, v246 offset:256
	s_or_b64 exec, exec, s[50:51]
	v_pk_add_f32 v[228:229], v[228:229], v[230:231]
	v_lshlrev_b32_e32 v210, 16, v192
	v_lshlrev_b32_e32 v211, 16, v193
	v_add_f32_e32 v232, v228, v229
	v_lshlrev_b32_e32 v212, 16, v194
	v_lshlrev_b32_e32 v213, 16, v195
	v_add_f32_dpp v232, v232, v232 quad_perm:[1,0,3,2] row_mask:0xf bank_mask:0xf bound_ctrl:1
	v_pk_fma_f32 v[234:235], v[40:41], v[192:193], v[40:41] neg_lo:[1,0,0] neg_hi:[1,0,0]
	v_pk_fma_f32 v[236:237], v[42:43], v[194:195], v[42:43] neg_lo:[1,0,0] neg_hi:[1,0,0]
	v_add_f32_dpp v232, v232, v232 quad_perm:[2,3,0,1] row_mask:0xf bank_mask:0xf bound_ctrl:1
	v_pk_fma_f32 v[238:239], v[44:45], v[210:211], v[44:45] neg_lo:[1,0,0] neg_hi:[1,0,0]
	v_pk_fma_f32 v[240:241], v[46:47], v[212:213], v[46:47] neg_lo:[1,0,0] neg_hi:[1,0,0]
	v_add_f32_dpp v232, v232, v232 row_half_mirror row_mask:0xf bank_mask:0xf bound_ctrl:1
	v_lshlrev_b32_e32 v226, 16, v204
	v_lshlrev_b32_e32 v214, 16, v196
	v_lshlrev_b32_e32 v215, 16, v197
	v_lshlrev_b32_e32 v216, 16, v198
	v_lshlrev_b32_e32 v217, 16, v199
	v_pk_fma_f32 v[234:235], v[226:227], v[196:197], v[234:235] op_sel_hi:[0,1,1]
	v_pk_fma_f32 v[236:237], v[226:227], v[198:199], v[236:237] op_sel_hi:[0,1,1]
	v_pk_fma_f32 v[238:239], v[226:227], v[214:215], v[238:239] op_sel_hi:[0,1,1]
	v_pk_fma_f32 v[240:241], v[226:227], v[216:217], v[240:241] op_sel_hi:[0,1,1]
	v_lshlrev_b32_e32 v218, 16, v200
	v_lshlrev_b32_e32 v219, 16, v201
	v_lshlrev_b32_e32 v220, 16, v202
	v_lshlrev_b32_e32 v221, 16, v203
	v_pk_fma_f32 v[40:41], v[232:233], v[200:201], v[234:235] op_sel_hi:[0,1,1] neg_lo:[1,0,0] neg_hi:[1,0,0]
	v_pk_fma_f32 v[42:43], v[232:233], v[202:203], v[236:237] op_sel_hi:[0,1,1] neg_lo:[1,0,0] neg_hi:[1,0,0]
	v_pk_fma_f32 v[44:45], v[232:233], v[218:219], v[238:239] op_sel_hi:[0,1,1] neg_lo:[1,0,0] neg_hi:[1,0,0]
	v_pk_fma_f32 v[46:47], v[232:233], v[220:221], v[240:241] op_sel_hi:[0,1,1] neg_lo:[1,0,0] neg_hi:[1,0,0]
	v_lshlrev_b32_e32 v222, 16, v184
	v_lshlrev_b32_e32 v223, 16, v185
	v_lshlrev_b32_e32 v224, 16, v186
	v_lshlrev_b32_e32 v225, 16, v187
	v_pk_mul_f32 v[242:243], v[40:41], v[184:185]
	v_pk_mul_f32 v[244:245], v[42:43], v[186:187]
	v_pk_fma_f32 v[242:243], v[44:45], v[222:223], v[242:243]
	v_pk_fma_f32 v[244:245], v[46:47], v[224:225], v[244:245]
	s_nop 0
	v_pk_add_f32 v[242:243], v[242:243], v[244:245]
	s_nop 0
	v_add_f32_e32 v248, v242, v243
	s_nop 1
	v_add_f32_dpp v248, v248, v248 quad_perm:[1,0,3,2] row_mask:0xf bank_mask:0xf bound_ctrl:1
	s_nop 1
	v_add_f32_dpp v248, v248, v248 quad_perm:[2,3,0,1] row_mask:0xf bank_mask:0xf bound_ctrl:1
	s_nop 1
	v_add_f32_dpp v248, v248, v248 row_half_mirror row_mask:0xf bank_mask:0xf bound_ctrl:1
	s_and_saveexec_b64 s[50:51], s[8:9]
	ds_write_b32 v63, v248 offset:384
	s_branch .LBB0_556

.LBB0_831:
	s_ashr_i32 s13, s12, 31
	s_lshl_b64 s[12:13], s[12:13], 12
	s_add_u32 s12, s10, s12
	s_addc_u32 s13, s11, s13
	s_ashr_i32 s19, s18, 31
	s_lshl_b64 s[10:11], s[18:19], 12
	s_add_u32 s10, s20, s10
	s_addc_u32 s11, s21, s11
	s_add_u32 s6, s8, s16
	s_addc_u32 s9, s9, s17
	s_add_u32 s8, s6, 0x176a000
	s_addc_u32 s9, s9, 0
	s_waitcnt vmcnt(0)
	v_and_b32_e32 v66, 15, v202
	v_lshl_add_u32 v66, v66, 3, s59
	v_lshlrev_b32_e32 v164, 2, v66
	global_load_dwordx4 v[84:87], v164, s[8:9]
	global_load_dwordx4 v[88:91], v164, s[8:9] offset:16
	v_lshrrev_b32_e32 v67, 4, v202
	v_lshlrev_b32_e32 v67, 12, v67
	v_lshl_add_u32 v165, v66, 2, v67
	v_lshl_add_u32 v166, v66, 1, v67
	v_mov_b32_e32 v68, v165
	v_add_u32_e32 v69, 0x10000, v165
	v_add_u32_e32 v70, 0x40000, v165
	v_add_u32_e32 v71, 0x50000, v165
	v_add_u32_e32 v72, 0x20000, v165
	v_add_u32_e32 v73, 0x30000, v165
	v_add_u32_e32 v74, 0x60000, v165
	v_add_u32_e32 v75, 0x70000, v165
	global_load_dwordx4 v[92:95], v68, s[12:13]
	global_load_dwordx4 v[96:99], v68, s[12:13] offset:16
	global_load_dwordx4 v[100:103], v69, s[12:13]
	global_load_dwordx4 v[104:107], v69, s[12:13] offset:16
	global_load_dwordx4 v[108:111], v70, s[12:13]
	global_load_dwordx4 v[112:115], v70, s[12:13] offset:16
	global_load_dwordx4 v[116:119], v71, s[12:13]
	global_load_dwordx4 v[120:123], v71, s[12:13] offset:16
	global_load_dwordx4 v[124:127], v72, s[12:13]
	global_load_dwordx4 v[128:131], v72, s[12:13] offset:16
	global_load_dwordx4 v[132:135], v73, s[12:13]
	global_load_dwordx4 v[136:139], v73, s[12:13] offset:16
	global_load_dwordx4 v[140:143], v74, s[12:13]
	global_load_dwordx4 v[144:147], v74, s[12:13] offset:16
	global_load_dwordx4 v[148:151], v75, s[12:13]
	global_load_dwordx4 v[152:155], v75, s[12:13] offset:16
	v_mov_b32_e32 v76, v166
	v_add_u32_e32 v77, 0x10000, v166
	v_add_u32_e32 v78, 0x40000, v166
	v_add_u32_e32 v79, 0x50000, v166
	v_add_u32_e32 v80, 0x20000, v166
	v_add_u32_e32 v81, 0x30000, v166
	v_add_u32_e32 v82, 0x60000, v166
	v_add_u32_e32 v83, 0x70000, v166
	v_lshrrev_b32_e32 v66, 7, v202
	v_bfe_u32 v67, v202, 5, 1
	v_lshlrev_b32_e32 v66, 5, v66
	v_lshl_or_b32 v66, v67, 2, v66
	v_mul_u32_u24_e32 v66, 132, v66
	v_and_b32_e32 v67, 0x5f, v202
	v_add_lshl_u32 v65, v66, v67, 2
	v_lshrrev_b32_e32 v66, 4, v202
	v_mul_u32_u24_e32 v66, 132, v66
	v_and_b32_e32 v67, 15, v202
	v_lshl_add_u32 v66, v67, 3, v66
	v_lshlrev_b32_e32 v64, 2, v66
	s_barrier
	ds_write_b32 v65, v48
	ds_write_b32 v65, v49 offset:528
	ds_write_b32 v65, v50 offset:1056
	ds_write_b32 v65, v51 offset:1584
	ds_write_b32 v65, v52 offset:4224
	ds_write_b32 v65, v53 offset:4752
	ds_write_b32 v65, v54 offset:5280
	ds_write_b32 v65, v55 offset:5808
	ds_write_b32 v65, v56 offset:8448
	ds_write_b32 v65, v57 offset:8976
	ds_write_b32 v65, v58 offset:9504
	ds_write_b32 v65, v59 offset:10032
	ds_write_b32 v65, v60 offset:12672
	ds_write_b32 v65, v61 offset:13200
	ds_write_b32 v65, v62 offset:13728
	ds_write_b32 v65, v63 offset:14256
	ds_write_b32 v65, v16 offset:128
	ds_write_b32 v65, v17 offset:656
	ds_write_b32 v65, v18 offset:1184
	ds_write_b32 v65, v19 offset:1712
	ds_write_b32 v65, v20 offset:4352
	ds_write_b32 v65, v21 offset:4880
	ds_write_b32 v65, v22 offset:5408
	ds_write_b32 v65, v23 offset:5936
	ds_write_b32 v65, v24 offset:8576
	ds_write_b32 v65, v25 offset:9104
	ds_write_b32 v65, v26 offset:9632
	ds_write_b32 v65, v27 offset:10160
	ds_write_b32 v65, v28 offset:12800
	ds_write_b32 v65, v29 offset:13328
	ds_write_b32 v65, v30 offset:13856
	ds_write_b32 v65, v31 offset:14384
	s_waitcnt lgkmcnt(0)
	s_barrier
	ds_read_b128 v[48:51], v64
	ds_read_b128 v[52:55], v64 offset:16
	ds_read_b128 v[56:59], v64 offset:8448
	ds_read_b128 v[60:63], v64 offset:8464
	ds_read_b128 v[16:19], v64 offset:16896
	ds_read_b128 v[20:23], v64 offset:16912
	ds_read_b128 v[24:27], v64 offset:25344
	ds_read_b128 v[28:31], v64 offset:25360
	s_waitcnt vmcnt(14) lgkmcnt(6)
	v_fma_f32 v48, v48, v84, v92
	v_fma_f32 v49, v49, v85, v93
	v_fma_f32 v50, v50, v86, v94
	v_fma_f32 v51, v51, v87, v95
	v_fma_f32 v52, v52, v88, v96
	v_fma_f32 v53, v53, v89, v97
	v_fma_f32 v54, v54, v90, v98
	v_fma_f32 v55, v55, v91, v99
	v_cvt_pk_bf16_f32 v48, v48, v49
	v_cvt_pk_bf16_f32 v49, v50, v51
	v_cvt_pk_bf16_f32 v50, v52, v53
	v_cvt_pk_bf16_f32 v51, v54, v55
	global_store_dwordx4 v76, v[48:51], s[10:11]
	s_waitcnt vmcnt(13) lgkmcnt(4)
	v_fma_f32 v56, v56, v84, v100
	v_fma_f32 v57, v57, v85, v101
	v_fma_f32 v58, v58, v86, v102
	v_fma_f32 v59, v59, v87, v103
	v_fma_f32 v60, v60, v88, v104
	v_fma_f32 v61, v61, v89, v105
	v_fma_f32 v62, v62, v90, v106
	v_fma_f32 v63, v63, v91, v107
	v_cvt_pk_bf16_f32 v56, v56, v57
	v_cvt_pk_bf16_f32 v57, v58, v59
	v_cvt_pk_bf16_f32 v58, v60, v61
	v_cvt_pk_bf16_f32 v59, v62, v63
	global_store_dwordx4 v77, v[56:59], s[10:11]
	s_waitcnt vmcnt(12) lgkmcnt(2)
	v_fma_f32 v16, v16, v84, v108
	v_fma_f32 v17, v17, v85, v109
	v_fma_f32 v18, v18, v86, v110
	v_fma_f32 v19, v19, v87, v111
	v_fma_f32 v20, v20, v88, v112
	v_fma_f32 v21, v21, v89, v113
	v_fma_f32 v22, v22, v90, v114
	v_fma_f32 v23, v23, v91, v115
	v_cvt_pk_bf16_f32 v16, v16, v17
	v_cvt_pk_bf16_f32 v17, v18, v19
	v_cvt_pk_bf16_f32 v18, v20, v21
	v_cvt_pk_bf16_f32 v19, v22, v23
	global_store_dwordx4 v78, v[16:19], s[10:11]
	s_waitcnt vmcnt(11) lgkmcnt(0)
	v_fma_f32 v24, v24, v84, v116
	v_fma_f32 v25, v25, v85, v117
	v_fma_f32 v26, v26, v86, v118
	v_fma_f32 v27, v27, v87, v119
	v_fma_f32 v28, v28, v88, v120
	v_fma_f32 v29, v29, v89, v121
	v_fma_f32 v30, v30, v90, v122
	v_fma_f32 v31, v31, v91, v123
	v_cvt_pk_bf16_f32 v24, v24, v25
	v_cvt_pk_bf16_f32 v25, v26, v27
	v_cvt_pk_bf16_f32 v26, v28, v29
	v_cvt_pk_bf16_f32 v27, v30, v31
	global_store_dwordx4 v79, v[24:27], s[10:11]
	s_barrier
	ds_write_b32 v65, v32
	ds_write_b32 v65, v33 offset:528
	ds_write_b32 v65, v34 offset:1056
	ds_write_b32 v65, v35 offset:1584
	ds_write_b32 v65, v36 offset:4224
	ds_write_b32 v65, v37 offset:4752
	ds_write_b32 v65, v38 offset:5280
	ds_write_b32 v65, v39 offset:5808
	ds_write_b32 v65, v40 offset:8448
	ds_write_b32 v65, v41 offset:8976
	ds_write_b32 v65, v42 offset:9504
	ds_write_b32 v65, v43 offset:10032
	ds_write_b32 v65, v44 offset:12672
	ds_write_b32 v65, v45 offset:13200
	ds_write_b32 v65, v46 offset:13728
	ds_write_b32 v65, v47 offset:14256
	ds_write_b32 v65, v0 offset:128
	ds_write_b32 v65, v1 offset:656
	ds_write_b32 v65, v2 offset:1184
	ds_write_b32 v65, v3 offset:1712
	ds_write_b32 v65, v4 offset:4352
	ds_write_b32 v65, v5 offset:4880
	ds_write_b32 v65, v6 offset:5408
	ds_write_b32 v65, v7 offset:5936
	ds_write_b32 v65, v8 offset:8576
	ds_write_b32 v65, v9 offset:9104
	ds_write_b32 v65, v10 offset:9632
	ds_write_b32 v65, v11 offset:10160
	ds_write_b32 v65, v12 offset:12800
	ds_write_b32 v65, v13 offset:13328
	ds_write_b32 v65, v14 offset:13856
	ds_write_b32 v65, v15 offset:14384
	s_waitcnt lgkmcnt(0)
	s_barrier
	ds_read_b128 v[32:35], v64
	ds_read_b128 v[36:39], v64 offset:16
	ds_read_b128 v[40:43], v64 offset:8448
	ds_read_b128 v[44:47], v64 offset:8464
	ds_read_b128 v[0:3], v64 offset:16896
	ds_read_b128 v[4:7], v64 offset:16912
	ds_read_b128 v[8:11], v64 offset:25344
	ds_read_b128 v[12:15], v64 offset:25360
	s_waitcnt vmcnt(10) lgkmcnt(6)
	v_fma_f32 v32, v32, v84, v124
	v_fma_f32 v33, v33, v85, v125
	v_fma_f32 v34, v34, v86, v126
	v_fma_f32 v35, v35, v87, v127
	v_fma_f32 v36, v36, v88, v128
	v_fma_f32 v37, v37, v89, v129
	v_fma_f32 v38, v38, v90, v130
	v_fma_f32 v39, v39, v91, v131
	v_cvt_pk_bf16_f32 v32, v32, v33
	v_cvt_pk_bf16_f32 v33, v34, v35
	v_cvt_pk_bf16_f32 v34, v36, v37
	v_cvt_pk_bf16_f32 v35, v38, v39
	global_store_dwordx4 v80, v[32:35], s[10:11]
	s_waitcnt vmcnt(9) lgkmcnt(4)
	v_fma_f32 v40, v40, v84, v132
	v_fma_f32 v41, v41, v85, v133
	v_fma_f32 v42, v42, v86, v134
	v_fma_f32 v43, v43, v87, v135
	v_fma_f32 v44, v44, v88, v136
	v_fma_f32 v45, v45, v89, v137
	v_fma_f32 v46, v46, v90, v138
	v_fma_f32 v47, v47, v91, v139
	v_cvt_pk_bf16_f32 v40, v40, v41
	v_cvt_pk_bf16_f32 v41, v42, v43
	v_cvt_pk_bf16_f32 v42, v44, v45
	v_cvt_pk_bf16_f32 v43, v46, v47
	global_store_dwordx4 v81, v[40:43], s[10:11]
	s_waitcnt vmcnt(8) lgkmcnt(2)
	v_fma_f32 v0, v0, v84, v140
	v_fma_f32 v1, v1, v85, v141
	v_fma_f32 v2, v2, v86, v142
	v_fma_f32 v3, v3, v87, v143
	v_fma_f32 v4, v4, v88, v144
	v_fma_f32 v5, v5, v89, v145
	v_fma_f32 v6, v6, v90, v146
	v_fma_f32 v7, v7, v91, v147
	v_cvt_pk_bf16_f32 v0, v0, v1
	v_cvt_pk_bf16_f32 v1, v2, v3
	v_cvt_pk_bf16_f32 v2, v4, v5
	v_cvt_pk_bf16_f32 v3, v6, v7
	global_store_dwordx4 v82, v[0:3], s[10:11]
	s_waitcnt vmcnt(7) lgkmcnt(0)
	v_fma_f32 v8, v8, v84, v148
	v_fma_f32 v9, v9, v85, v149
	v_fma_f32 v10, v10, v86, v150
	v_fma_f32 v11, v11, v87, v151
	v_fma_f32 v12, v12, v88, v152
	v_fma_f32 v13, v13, v89, v153
	v_fma_f32 v14, v14, v90, v154
	v_fma_f32 v15, v15, v91, v155
	v_cvt_pk_bf16_f32 v8, v8, v9
	v_cvt_pk_bf16_f32 v9, v10, v11
	v_cvt_pk_bf16_f32 v10, v12, v13
	v_cvt_pk_bf16_f32 v11, v14, v15
	global_store_dwordx4 v83, v[8:11], s[10:11]
	s_add_i32 s58, s58, s26
	s_add_i32 s57, s57, s34
	s_cmpk_gt_u32 s58, 0x11f
	s_cbranch_scc1 .LBB0_825

.LBB0_1064:
	s_ashr_i32 s11, s10, 31
	s_lshl_b64 s[10:11], s[10:11], 12
	s_add_u32 s12, s12, s10
	s_addc_u32 s13, s13, s11
	s_ashr_i32 s19, s18, 31
	s_lshl_b64 s[10:11], s[18:19], 12
	s_add_u32 s10, s20, s10
	s_addc_u32 s11, s21, s11
	s_add_u32 s0, s8, s16
	s_addc_u32 s9, s9, s17
	s_add_u32 s8, s0, 0x176d000
	s_addc_u32 s9, s9, 0
	s_waitcnt vmcnt(0)
	v_and_b32_e32 v66, 15, v202
	v_lshl_add_u32 v66, v66, 3, s62
	v_lshlrev_b32_e32 v164, 2, v66
	global_load_dwordx4 v[84:87], v164, s[8:9]
	global_load_dwordx4 v[88:91], v164, s[8:9] offset:16
	v_lshrrev_b32_e32 v67, 4, v202
	v_lshlrev_b32_e32 v67, 12, v67
	v_lshl_add_u32 v165, v66, 1, v67
	v_mov_b32_e32 v68, v165
	v_add_u32_e32 v69, 0x10000, v165
	v_add_u32_e32 v70, 0x40000, v165
	v_add_u32_e32 v71, 0x50000, v165
	v_add_u32_e32 v72, 0x20000, v165
	v_add_u32_e32 v73, 0x30000, v165
	v_add_u32_e32 v74, 0x60000, v165
	v_add_u32_e32 v75, 0x70000, v165
	global_load_dwordx4 v[92:95], v68, s[12:13]
	global_load_dwordx4 v[96:99], v69, s[12:13]
	global_load_dwordx4 v[100:103], v70, s[12:13]
	global_load_dwordx4 v[104:107], v71, s[12:13]
	global_load_dwordx4 v[108:111], v72, s[12:13]
	global_load_dwordx4 v[112:115], v73, s[12:13]
	global_load_dwordx4 v[116:119], v74, s[12:13]
	global_load_dwordx4 v[120:123], v75, s[12:13]
	v_lshrrev_b32_e32 v66, 7, v202
	v_bfe_u32 v67, v202, 5, 1
	v_lshlrev_b32_e32 v66, 5, v66
	v_lshl_or_b32 v66, v67, 2, v66
	v_mul_u32_u24_e32 v66, 132, v66
	v_and_b32_e32 v67, 0x5f, v202
	v_add_lshl_u32 v65, v66, v67, 2
	v_lshrrev_b32_e32 v66, 4, v202
	v_mul_u32_u24_e32 v66, 132, v66
	v_and_b32_e32 v67, 15, v202
	v_lshl_add_u32 v66, v67, 3, v66
	v_lshlrev_b32_e32 v64, 2, v66
	s_barrier
	ds_write_b32 v65, v48
	ds_write_b32 v65, v49 offset:528
	ds_write_b32 v65, v50 offset:1056
	ds_write_b32 v65, v51 offset:1584
	ds_write_b32 v65, v52 offset:4224
	ds_write_b32 v65, v53 offset:4752
	ds_write_b32 v65, v54 offset:5280
	ds_write_b32 v65, v55 offset:5808
	ds_write_b32 v65, v56 offset:8448
	ds_write_b32 v65, v57 offset:8976
	ds_write_b32 v65, v58 offset:9504
	ds_write_b32 v65, v59 offset:10032
	ds_write_b32 v65, v60 offset:12672
	ds_write_b32 v65, v61 offset:13200
	ds_write_b32 v65, v62 offset:13728
	ds_write_b32 v65, v63 offset:14256
	ds_write_b32 v65, v16 offset:128
	ds_write_b32 v65, v17 offset:656
	ds_write_b32 v65, v18 offset:1184
	ds_write_b32 v65, v19 offset:1712
	ds_write_b32 v65, v20 offset:4352
	ds_write_b32 v65, v21 offset:4880
	ds_write_b32 v65, v22 offset:5408
	ds_write_b32 v65, v23 offset:5936
	ds_write_b32 v65, v24 offset:8576
	ds_write_b32 v65, v25 offset:9104
	ds_write_b32 v65, v26 offset:9632
	ds_write_b32 v65, v27 offset:10160
	ds_write_b32 v65, v28 offset:12800
	ds_write_b32 v65, v29 offset:13328
	ds_write_b32 v65, v30 offset:13856
	ds_write_b32 v65, v31 offset:14384
	s_waitcnt lgkmcnt(0)
	s_barrier
	ds_read_b128 v[48:51], v64
	ds_read_b128 v[52:55], v64 offset:16
	ds_read_b128 v[56:59], v64 offset:8448
	ds_read_b128 v[60:63], v64 offset:8464
	ds_read_b128 v[16:19], v64 offset:16896
	ds_read_b128 v[20:23], v64 offset:16912
	ds_read_b128 v[24:27], v64 offset:25344
	ds_read_b128 v[28:31], v64 offset:25360
	s_waitcnt vmcnt(7) lgkmcnt(6)
	v_lshlrev_b32_e32 v167, 16, v92
	v_and_b32_e32 v168, 0xffff0000, v92
	v_fma_f32 v48, v48, v84, v167
	v_fma_f32 v49, v49, v85, v168
	v_lshlrev_b32_e32 v167, 16, v93
	v_and_b32_e32 v168, 0xffff0000, v93
	v_fma_f32 v50, v50, v86, v167
	v_fma_f32 v51, v51, v87, v168
	v_lshlrev_b32_e32 v167, 16, v94
	v_and_b32_e32 v168, 0xffff0000, v94
	v_fma_f32 v52, v52, v88, v167
	v_fma_f32 v53, v53, v89, v168
	v_lshlrev_b32_e32 v167, 16, v95
	v_and_b32_e32 v168, 0xffff0000, v95
	v_fma_f32 v54, v54, v90, v167
	v_fma_f32 v55, v55, v91, v168
	v_cvt_pk_bf16_f32 v48, v48, v49
	v_cvt_pk_bf16_f32 v49, v50, v51
	v_cvt_pk_bf16_f32 v50, v52, v53
	v_cvt_pk_bf16_f32 v51, v54, v55
	global_store_dwordx4 v68, v[48:51], s[10:11]
	s_waitcnt vmcnt(7) lgkmcnt(4)
	v_lshlrev_b32_e32 v167, 16, v96
	v_and_b32_e32 v168, 0xffff0000, v96
	v_fma_f32 v56, v56, v84, v167
	v_fma_f32 v57, v57, v85, v168
	v_lshlrev_b32_e32 v167, 16, v97
	v_and_b32_e32 v168, 0xffff0000, v97
	v_fma_f32 v58, v58, v86, v167
	v_fma_f32 v59, v59, v87, v168
	v_lshlrev_b32_e32 v167, 16, v98
	v_and_b32_e32 v168, 0xffff0000, v98
	v_fma_f32 v60, v60, v88, v167
	v_fma_f32 v61, v61, v89, v168
	v_lshlrev_b32_e32 v167, 16, v99
	v_and_b32_e32 v168, 0xffff0000, v99
	v_fma_f32 v62, v62, v90, v167
	v_fma_f32 v63, v63, v91, v168
	v_cvt_pk_bf16_f32 v56, v56, v57
	v_cvt_pk_bf16_f32 v57, v58, v59
	v_cvt_pk_bf16_f32 v58, v60, v61
	v_cvt_pk_bf16_f32 v59, v62, v63
	global_store_dwordx4 v69, v[56:59], s[10:11]
	s_waitcnt vmcnt(7) lgkmcnt(2)
	v_lshlrev_b32_e32 v167, 16, v100
	v_and_b32_e32 v168, 0xffff0000, v100
	v_fma_f32 v16, v16, v84, v167
	v_fma_f32 v17, v17, v85, v168
	v_lshlrev_b32_e32 v167, 16, v101
	v_and_b32_e32 v168, 0xffff0000, v101
	v_fma_f32 v18, v18, v86, v167
	v_fma_f32 v19, v19, v87, v168
	v_lshlrev_b32_e32 v167, 16, v102
	v_and_b32_e32 v168, 0xffff0000, v102
	v_fma_f32 v20, v20, v88, v167
	v_fma_f32 v21, v21, v89, v168
	v_lshlrev_b32_e32 v167, 16, v103
	v_and_b32_e32 v168, 0xffff0000, v103
	v_fma_f32 v22, v22, v90, v167
	v_fma_f32 v23, v23, v91, v168
	v_cvt_pk_bf16_f32 v16, v16, v17
	v_cvt_pk_bf16_f32 v17, v18, v19
	v_cvt_pk_bf16_f32 v18, v20, v21
	v_cvt_pk_bf16_f32 v19, v22, v23
	global_store_dwordx4 v70, v[16:19], s[10:11]
	s_waitcnt vmcnt(7) lgkmcnt(0)
	v_lshlrev_b32_e32 v167, 16, v104
	v_and_b32_e32 v168, 0xffff0000, v104
	v_fma_f32 v24, v24, v84, v167
	v_fma_f32 v25, v25, v85, v168
	v_lshlrev_b32_e32 v167, 16, v105
	v_and_b32_e32 v168, 0xffff0000, v105
	v_fma_f32 v26, v26, v86, v167
	v_fma_f32 v27, v27, v87, v168
	v_lshlrev_b32_e32 v167, 16, v106
	v_and_b32_e32 v168, 0xffff0000, v106
	v_fma_f32 v28, v28, v88, v167
	v_fma_f32 v29, v29, v89, v168
	v_lshlrev_b32_e32 v167, 16, v107
	v_and_b32_e32 v168, 0xffff0000, v107
	v_fma_f32 v30, v30, v90, v167
	v_fma_f32 v31, v31, v91, v168
	v_cvt_pk_bf16_f32 v24, v24, v25
	v_cvt_pk_bf16_f32 v25, v26, v27
	v_cvt_pk_bf16_f32 v26, v28, v29
	v_cvt_pk_bf16_f32 v27, v30, v31
	global_store_dwordx4 v71, v[24:27], s[10:11]
	s_barrier
	ds_write_b32 v65, v32
	ds_write_b32 v65, v33 offset:528
	ds_write_b32 v65, v34 offset:1056
	ds_write_b32 v65, v35 offset:1584
	ds_write_b32 v65, v36 offset:4224
	ds_write_b32 v65, v37 offset:4752
	ds_write_b32 v65, v38 offset:5280
	ds_write_b32 v65, v39 offset:5808
	ds_write_b32 v65, v40 offset:8448
	ds_write_b32 v65, v41 offset:8976
	ds_write_b32 v65, v42 offset:9504
	ds_write_b32 v65, v43 offset:10032
	ds_write_b32 v65, v44 offset:12672
	ds_write_b32 v65, v45 offset:13200
	ds_write_b32 v65, v46 offset:13728
	ds_write_b32 v65, v47 offset:14256
	ds_write_b32 v65, v0 offset:128
	ds_write_b32 v65, v1 offset:656
	ds_write_b32 v65, v2 offset:1184
	ds_write_b32 v65, v3 offset:1712
	ds_write_b32 v65, v4 offset:4352
	ds_write_b32 v65, v5 offset:4880
	ds_write_b32 v65, v6 offset:5408
	ds_write_b32 v65, v7 offset:5936
	ds_write_b32 v65, v8 offset:8576
	ds_write_b32 v65, v9 offset:9104
	ds_write_b32 v65, v10 offset:9632
	ds_write_b32 v65, v11 offset:10160
	ds_write_b32 v65, v12 offset:12800
	ds_write_b32 v65, v13 offset:13328
	ds_write_b32 v65, v14 offset:13856
	ds_write_b32 v65, v15 offset:14384
	s_waitcnt lgkmcnt(0)
	s_barrier
	ds_read_b128 v[32:35], v64
	ds_read_b128 v[36:39], v64 offset:16
	ds_read_b128 v[40:43], v64 offset:8448
	ds_read_b128 v[44:47], v64 offset:8464
	ds_read_b128 v[0:3], v64 offset:16896
	ds_read_b128 v[4:7], v64 offset:16912
	ds_read_b128 v[8:11], v64 offset:25344
	ds_read_b128 v[12:15], v64 offset:25360
	s_waitcnt vmcnt(7) lgkmcnt(6)
	v_lshlrev_b32_e32 v167, 16, v108
	v_and_b32_e32 v168, 0xffff0000, v108
	v_fma_f32 v32, v32, v84, v167
	v_fma_f32 v33, v33, v85, v168
	v_lshlrev_b32_e32 v167, 16, v109
	v_and_b32_e32 v168, 0xffff0000, v109
	v_fma_f32 v34, v34, v86, v167
	v_fma_f32 v35, v35, v87, v168
	v_lshlrev_b32_e32 v167, 16, v110
	v_and_b32_e32 v168, 0xffff0000, v110
	v_fma_f32 v36, v36, v88, v167
	v_fma_f32 v37, v37, v89, v168
	v_lshlrev_b32_e32 v167, 16, v111
	v_and_b32_e32 v168, 0xffff0000, v111
	v_fma_f32 v38, v38, v90, v167
	v_fma_f32 v39, v39, v91, v168
	v_cvt_pk_bf16_f32 v32, v32, v33
	v_cvt_pk_bf16_f32 v33, v34, v35
	v_cvt_pk_bf16_f32 v34, v36, v37
	v_cvt_pk_bf16_f32 v35, v38, v39
	global_store_dwordx4 v72, v[32:35], s[10:11]
	s_waitcnt vmcnt(7) lgkmcnt(4)
	v_lshlrev_b32_e32 v167, 16, v112
	v_and_b32_e32 v168, 0xffff0000, v112
	v_fma_f32 v40, v40, v84, v167
	v_fma_f32 v41, v41, v85, v168
	v_lshlrev_b32_e32 v167, 16, v113
	v_and_b32_e32 v168, 0xffff0000, v113
	v_fma_f32 v42, v42, v86, v167
	v_fma_f32 v43, v43, v87, v168
	v_lshlrev_b32_e32 v167, 16, v114
	v_and_b32_e32 v168, 0xffff0000, v114
	v_fma_f32 v44, v44, v88, v167
	v_fma_f32 v45, v45, v89, v168
	v_lshlrev_b32_e32 v167, 16, v115
	v_and_b32_e32 v168, 0xffff0000, v115
	v_fma_f32 v46, v46, v90, v167
	v_fma_f32 v47, v47, v91, v168
	v_cvt_pk_bf16_f32 v40, v40, v41
	v_cvt_pk_bf16_f32 v41, v42, v43
	v_cvt_pk_bf16_f32 v42, v44, v45
	v_cvt_pk_bf16_f32 v43, v46, v47
	global_store_dwordx4 v73, v[40:43], s[10:11]
	s_waitcnt vmcnt(7) lgkmcnt(2)
	v_lshlrev_b32_e32 v167, 16, v116
	v_and_b32_e32 v168, 0xffff0000, v116
	v_fma_f32 v0, v0, v84, v167
	v_fma_f32 v1, v1, v85, v168
	v_lshlrev_b32_e32 v167, 16, v117
	v_and_b32_e32 v168, 0xffff0000, v117
	v_fma_f32 v2, v2, v86, v167
	v_fma_f32 v3, v3, v87, v168
	v_lshlrev_b32_e32 v167, 16, v118
	v_and_b32_e32 v168, 0xffff0000, v118
	v_fma_f32 v4, v4, v88, v167
	v_fma_f32 v5, v5, v89, v168
	v_lshlrev_b32_e32 v167, 16, v119
	v_and_b32_e32 v168, 0xffff0000, v119
	v_fma_f32 v6, v6, v90, v167
	v_fma_f32 v7, v7, v91, v168
	v_cvt_pk_bf16_f32 v0, v0, v1
	v_cvt_pk_bf16_f32 v1, v2, v3
	v_cvt_pk_bf16_f32 v2, v4, v5
	v_cvt_pk_bf16_f32 v3, v6, v7
	global_store_dwordx4 v74, v[0:3], s[10:11]
	s_waitcnt vmcnt(7) lgkmcnt(0)
	v_lshlrev_b32_e32 v167, 16, v120
	v_and_b32_e32 v168, 0xffff0000, v120
	v_fma_f32 v8, v8, v84, v167
	v_fma_f32 v9, v9, v85, v168
	v_lshlrev_b32_e32 v167, 16, v121
	v_and_b32_e32 v168, 0xffff0000, v121
	v_fma_f32 v10, v10, v86, v167
	v_fma_f32 v11, v11, v87, v168
	v_lshlrev_b32_e32 v167, 16, v122
	v_and_b32_e32 v168, 0xffff0000, v122
	v_fma_f32 v12, v12, v88, v167
	v_fma_f32 v13, v13, v89, v168
	v_lshlrev_b32_e32 v167, 16, v123
	v_and_b32_e32 v168, 0xffff0000, v123
	v_fma_f32 v14, v14, v90, v167
	v_fma_f32 v15, v15, v91, v168
	v_cvt_pk_bf16_f32 v8, v8, v9
	v_cvt_pk_bf16_f32 v9, v10, v11
	v_cvt_pk_bf16_f32 v10, v12, v13
	v_cvt_pk_bf16_f32 v11, v14, v15
	global_store_dwordx4 v75, v[8:11], s[10:11]
	s_add_i32 s61, s61, s34
	s_add_i32 s60, s60, s36
	s_cmpk_gt_u32 s61, 0x11f
	s_cbranch_scc1 .LBB0_1058

.LBB0_1540:
	v_add_u32_e32 v65, s16, v62
	ds_read_u16 v204, v65 offset:64
	ds_read_b128 v[184:187], v64 offset:640
	ds_read_b128 v[188:191], v64 offset:768
	ds_read_b128 v[192:195], v64 offset:896
	ds_read_b128 v[196:199], v64 offset:1024
	ds_read_b128 v[200:203], v64 offset:1152
	s_waitcnt lgkmcnt(6)
	v_lshlrev_b32_e32 v206, 16, v166
	v_lshlrev_b32_e32 v207, 16, v167
	v_lshlrev_b32_e32 v208, 16, v168
	v_lshlrev_b32_e32 v209, 16, v169
	v_pk_mul_f32 v[228:229], v[44:45], v[206:207]
	v_pk_mul_f32 v[230:231], v[46:47], v[208:209]
	v_pk_fma_f32 v[228:229], v[40:41], v[166:167], v[228:229]
	v_pk_fma_f32 v[230:231], v[42:43], v[168:169], v[230:231]
	v_lshlrev_b32_e32 v210, 16, v170
	v_pk_add_f32 v[228:229], v[228:229], v[230:231]
	v_lshlrev_b32_e32 v211, 16, v171
	v_add_f32_e32 v232, v228, v229
	v_lshlrev_b32_e32 v212, 16, v172
	v_lshlrev_b32_e32 v213, 16, v173
	v_add_f32_dpp v232, v232, v232 quad_perm:[1,0,3,2] row_mask:0xf bank_mask:0xf bound_ctrl:1
	v_pk_fma_f32 v[234:235], v[40:41], v[170:171], v[40:41] neg_lo:[1,0,0] neg_hi:[1,0,0]
	v_pk_fma_f32 v[236:237], v[42:43], v[172:173], v[42:43] neg_lo:[1,0,0] neg_hi:[1,0,0]
	v_add_f32_dpp v232, v232, v232 quad_perm:[2,3,0,1] row_mask:0xf bank_mask:0xf bound_ctrl:1
	v_pk_fma_f32 v[238:239], v[44:45], v[210:211], v[44:45] neg_lo:[1,0,0] neg_hi:[1,0,0]
	v_pk_fma_f32 v[240:241], v[46:47], v[212:213], v[46:47] neg_lo:[1,0,0] neg_hi:[1,0,0]
	v_add_f32_dpp v232, v232, v232 row_half_mirror row_mask:0xf bank_mask:0xf bound_ctrl:1
	v_lshlrev_b32_e32 v226, 16, v182
	v_lshlrev_b32_e32 v214, 16, v174
	v_lshlrev_b32_e32 v215, 16, v175
	v_lshlrev_b32_e32 v216, 16, v176
	v_lshlrev_b32_e32 v217, 16, v177
	v_pk_fma_f32 v[234:235], v[226:227], v[174:175], v[234:235] op_sel_hi:[0,1,1]
	v_pk_fma_f32 v[236:237], v[226:227], v[176:177], v[236:237] op_sel_hi:[0,1,1]
	v_pk_fma_f32 v[238:239], v[226:227], v[214:215], v[238:239] op_sel_hi:[0,1,1]
	v_pk_fma_f32 v[240:241], v[226:227], v[216:217], v[240:241] op_sel_hi:[0,1,1]
	v_lshlrev_b32_e32 v218, 16, v178
	v_lshlrev_b32_e32 v219, 16, v179
	v_lshlrev_b32_e32 v220, 16, v180
	v_lshlrev_b32_e32 v221, 16, v181
	v_pk_fma_f32 v[40:41], v[232:233], v[178:179], v[234:235] op_sel_hi:[0,1,1] neg_lo:[1,0,0] neg_hi:[1,0,0]
	v_pk_fma_f32 v[42:43], v[232:233], v[180:181], v[236:237] op_sel_hi:[0,1,1] neg_lo:[1,0,0] neg_hi:[1,0,0]
	v_pk_fma_f32 v[44:45], v[232:233], v[218:219], v[238:239] op_sel_hi:[0,1,1] neg_lo:[1,0,0] neg_hi:[1,0,0]
	v_pk_fma_f32 v[46:47], v[232:233], v[220:221], v[240:241] op_sel_hi:[0,1,1] neg_lo:[1,0,0] neg_hi:[1,0,0]
	v_lshlrev_b32_e32 v222, 16, v162
	v_lshlrev_b32_e32 v223, 16, v163
	v_lshlrev_b32_e32 v224, 16, v164
	v_lshlrev_b32_e32 v225, 16, v165
	v_pk_mul_f32 v[242:243], v[40:41], v[162:163]
	v_pk_mul_f32 v[244:245], v[42:43], v[164:165]
	v_pk_fma_f32 v[242:243], v[44:45], v[222:223], v[242:243]
	v_pk_fma_f32 v[244:245], v[46:47], v[224:225], v[244:245]
	ds_read_u16 v182, v65 offset:128
	ds_read_b128 v[162:165], v64 offset:1280
	ds_read_b128 v[166:169], v64 offset:1408
	ds_read_b128 v[170:173], v64 offset:1536
	ds_read_b128 v[174:177], v64 offset:1664
	ds_read_b128 v[178:181], v64 offset:1792
	v_pk_add_f32 v[242:243], v[242:243], v[244:245]
	s_waitcnt lgkmcnt(6)
	v_lshlrev_b32_e32 v206, 16, v188
	v_add_f32_e32 v246, v242, v243
	v_lshlrev_b32_e32 v207, 16, v189
	v_lshlrev_b32_e32 v208, 16, v190
	v_add_f32_dpp v246, v246, v246 quad_perm:[1,0,3,2] row_mask:0xf bank_mask:0xf bound_ctrl:1
	v_lshlrev_b32_e32 v209, 16, v191
	v_pk_mul_f32 v[228:229], v[44:45], v[206:207]
	v_add_f32_dpp v246, v246, v246 quad_perm:[2,3,0,1] row_mask:0xf bank_mask:0xf bound_ctrl:1
	v_pk_mul_f32 v[230:231], v[46:47], v[208:209]
	v_pk_fma_f32 v[228:229], v[40:41], v[188:189], v[228:229]
	v_add_f32_dpp v246, v246, v246 row_half_mirror row_mask:0xf bank_mask:0xf bound_ctrl:1
	v_pk_fma_f32 v[230:231], v[42:43], v[190:191], v[230:231]
	s_and_saveexec_b64 s[52:53], s[8:9]
	ds_write_b32 v63, v246
	s_or_b64 exec, exec, s[52:53]
	v_pk_add_f32 v[228:229], v[228:229], v[230:231]
	v_lshlrev_b32_e32 v210, 16, v192
	v_lshlrev_b32_e32 v211, 16, v193
	v_add_f32_e32 v232, v228, v229
	v_lshlrev_b32_e32 v212, 16, v194
	v_lshlrev_b32_e32 v213, 16, v195
	v_add_f32_dpp v232, v232, v232 quad_perm:[1,0,3,2] row_mask:0xf bank_mask:0xf bound_ctrl:1
	v_pk_fma_f32 v[234:235], v[40:41], v[192:193], v[40:41] neg_lo:[1,0,0] neg_hi:[1,0,0]
	v_pk_fma_f32 v[236:237], v[42:43], v[194:195], v[42:43] neg_lo:[1,0,0] neg_hi:[1,0,0]
	v_add_f32_dpp v232, v232, v232 quad_perm:[2,3,0,1] row_mask:0xf bank_mask:0xf bound_ctrl:1
	v_pk_fma_f32 v[238:239], v[44:45], v[210:211], v[44:45] neg_lo:[1,0,0] neg_hi:[1,0,0]
	v_pk_fma_f32 v[240:241], v[46:47], v[212:213], v[46:47] neg_lo:[1,0,0] neg_hi:[1,0,0]
	v_add_f32_dpp v232, v232, v232 row_half_mirror row_mask:0xf bank_mask:0xf bound_ctrl:1
	v_lshlrev_b32_e32 v226, 16, v204
	v_lshlrev_b32_e32 v214, 16, v196
	v_lshlrev_b32_e32 v215, 16, v197
	v_lshlrev_b32_e32 v216, 16, v198
	v_lshlrev_b32_e32 v217, 16, v199
	v_pk_fma_f32 v[234:235], v[226:227], v[196:197], v[234:235] op_sel_hi:[0,1,1]
	v_pk_fma_f32 v[236:237], v[226:227], v[198:199], v[236:237] op_sel_hi:[0,1,1]
	v_pk_fma_f32 v[238:239], v[226:227], v[214:215], v[238:239] op_sel_hi:[0,1,1]
	v_pk_fma_f32 v[240:241], v[226:227], v[216:217], v[240:241] op_sel_hi:[0,1,1]
	v_lshlrev_b32_e32 v218, 16, v200
	v_lshlrev_b32_e32 v219, 16, v201
	v_lshlrev_b32_e32 v220, 16, v202
	v_lshlrev_b32_e32 v221, 16, v203
	v_pk_fma_f32 v[40:41], v[232:233], v[200:201], v[234:235] op_sel_hi:[0,1,1] neg_lo:[1,0,0] neg_hi:[1,0,0]
	v_pk_fma_f32 v[42:43], v[232:233], v[202:203], v[236:237] op_sel_hi:[0,1,1] neg_lo:[1,0,0] neg_hi:[1,0,0]
	v_pk_fma_f32 v[44:45], v[232:233], v[218:219], v[238:239] op_sel_hi:[0,1,1] neg_lo:[1,0,0] neg_hi:[1,0,0]
	v_pk_fma_f32 v[46:47], v[232:233], v[220:221], v[240:241] op_sel_hi:[0,1,1] neg_lo:[1,0,0] neg_hi:[1,0,0]
	v_lshlrev_b32_e32 v222, 16, v184
	v_lshlrev_b32_e32 v223, 16, v185
	v_lshlrev_b32_e32 v224, 16, v186
	v_lshlrev_b32_e32 v225, 16, v187
	v_pk_mul_f32 v[242:243], v[40:41], v[184:185]
	v_pk_mul_f32 v[244:245], v[42:43], v[186:187]
	v_pk_fma_f32 v[242:243], v[44:45], v[222:223], v[242:243]
	v_pk_fma_f32 v[244:245], v[46:47], v[224:225], v[244:245]
	ds_read_u16 v204, v65 offset:192
	ds_read_b128 v[184:187], v64 offset:1920
	ds_read_b128 v[188:191], v64 offset:2048
	ds_read_b128 v[192:195], v64 offset:2176
	ds_read_b128 v[196:199], v64 offset:2304
	ds_read_b128 v[200:203], v64 offset:2432
	v_pk_add_f32 v[242:243], v[242:243], v[244:245]
	s_waitcnt lgkmcnt(6)
	v_lshlrev_b32_e32 v206, 16, v166
	v_add_f32_e32 v248, v242, v243
	v_lshlrev_b32_e32 v207, 16, v167
	v_lshlrev_b32_e32 v208, 16, v168
	v_add_f32_dpp v248, v248, v248 quad_perm:[1,0,3,2] row_mask:0xf bank_mask:0xf bound_ctrl:1
	v_lshlrev_b32_e32 v209, 16, v169
	v_pk_mul_f32 v[228:229], v[44:45], v[206:207]
	v_add_f32_dpp v248, v248, v248 quad_perm:[2,3,0,1] row_mask:0xf bank_mask:0xf bound_ctrl:1
	v_pk_mul_f32 v[230:231], v[46:47], v[208:209]
	v_pk_fma_f32 v[228:229], v[40:41], v[166:167], v[228:229]
	v_add_f32_dpp v248, v248, v248 row_half_mirror row_mask:0xf bank_mask:0xf bound_ctrl:1
	v_pk_fma_f32 v[230:231], v[42:43], v[168:169], v[230:231]
	s_and_saveexec_b64 s[52:53], s[8:9]
	ds_write_b32 v63, v248 offset:128
	s_or_b64 exec, exec, s[52:53]
	v_pk_add_f32 v[228:229], v[228:229], v[230:231]
	v_lshlrev_b32_e32 v210, 16, v170
	v_lshlrev_b32_e32 v211, 16, v171
	v_add_f32_e32 v232, v228, v229
	v_lshlrev_b32_e32 v212, 16, v172
	v_lshlrev_b32_e32 v213, 16, v173
	v_add_f32_dpp v232, v232, v232 quad_perm:[1,0,3,2] row_mask:0xf bank_mask:0xf bound_ctrl:1
	v_pk_fma_f32 v[234:235], v[40:41], v[170:171], v[40:41] neg_lo:[1,0,0] neg_hi:[1,0,0]
	v_pk_fma_f32 v[236:237], v[42:43], v[172:173], v[42:43] neg_lo:[1,0,0] neg_hi:[1,0,0]
	v_add_f32_dpp v232, v232, v232 quad_perm:[2,3,0,1] row_mask:0xf bank_mask:0xf bound_ctrl:1
	v_pk_fma_f32 v[238:239], v[44:45], v[210:211], v[44:45] neg_lo:[1,0,0] neg_hi:[1,0,0]
	v_pk_fma_f32 v[240:241], v[46:47], v[212:213], v[46:47] neg_lo:[1,0,0] neg_hi:[1,0,0]
	v_add_f32_dpp v232, v232, v232 row_half_mirror row_mask:0xf bank_mask:0xf bound_ctrl:1
	v_lshlrev_b32_e32 v226, 16, v182
	v_lshlrev_b32_e32 v214, 16, v174
	v_lshlrev_b32_e32 v215, 16, v175
	v_lshlrev_b32_e32 v216, 16, v176
	v_lshlrev_b32_e32 v217, 16, v177
	v_pk_fma_f32 v[234:235], v[226:227], v[174:175], v[234:235] op_sel_hi:[0,1,1]
	v_pk_fma_f32 v[236:237], v[226:227], v[176:177], v[236:237] op_sel_hi:[0,1,1]
	v_pk_fma_f32 v[238:239], v[226:227], v[214:215], v[238:239] op_sel_hi:[0,1,1]
	v_pk_fma_f32 v[240:241], v[226:227], v[216:217], v[240:241] op_sel_hi:[0,1,1]
	v_lshlrev_b32_e32 v218, 16, v178
	v_lshlrev_b32_e32 v219, 16, v179
	v_lshlrev_b32_e32 v220, 16, v180
	v_lshlrev_b32_e32 v221, 16, v181
	v_pk_fma_f32 v[40:41], v[232:233], v[178:179], v[234:235] op_sel_hi:[0,1,1] neg_lo:[1,0,0] neg_hi:[1,0,0]
	v_pk_fma_f32 v[42:43], v[232:233], v[180:181], v[236:237] op_sel_hi:[0,1,1] neg_lo:[1,0,0] neg_hi:[1,0,0]
	v_pk_fma_f32 v[44:45], v[232:233], v[218:219], v[238:239] op_sel_hi:[0,1,1] neg_lo:[1,0,0] neg_hi:[1,0,0]
	v_pk_fma_f32 v[46:47], v[232:233], v[220:221], v[240:241] op_sel_hi:[0,1,1] neg_lo:[1,0,0] neg_hi:[1,0,0]
	v_lshlrev_b32_e32 v222, 16, v162
	v_lshlrev_b32_e32 v223, 16, v163
	v_lshlrev_b32_e32 v224, 16, v164
	v_lshlrev_b32_e32 v225, 16, v165
	v_pk_mul_f32 v[242:243], v[40:41], v[162:163]
	v_pk_mul_f32 v[244:245], v[42:43], v[164:165]
	v_pk_fma_f32 v[242:243], v[44:45], v[222:223], v[242:243]
	v_pk_fma_f32 v[244:245], v[46:47], v[224:225], v[244:245]
	ds_read_u16 v182, v65 offset:256
	ds_read_b128 v[162:165], v64 offset:2560
	ds_read_b128 v[166:169], v64 offset:2688
	ds_read_b128 v[170:173], v64 offset:2816
	ds_read_b128 v[174:177], v64 offset:2944
	ds_read_b128 v[178:181], v64 offset:3072
	v_pk_add_f32 v[242:243], v[242:243], v[244:245]
	s_waitcnt lgkmcnt(6)
	v_lshlrev_b32_e32 v206, 16, v188
	v_add_f32_e32 v246, v242, v243
	v_lshlrev_b32_e32 v207, 16, v189
	v_lshlrev_b32_e32 v208, 16, v190
	v_add_f32_dpp v246, v246, v246 quad_perm:[1,0,3,2] row_mask:0xf bank_mask:0xf bound_ctrl:1
	v_lshlrev_b32_e32 v209, 16, v191
	v_pk_mul_f32 v[228:229], v[44:45], v[206:207]
	v_add_f32_dpp v246, v246, v246 quad_perm:[2,3,0,1] row_mask:0xf bank_mask:0xf bound_ctrl:1
	v_pk_mul_f32 v[230:231], v[46:47], v[208:209]
	v_pk_fma_f32 v[228:229], v[40:41], v[188:189], v[228:229]
	v_add_f32_dpp v246, v246, v246 row_half_mirror row_mask:0xf bank_mask:0xf bound_ctrl:1
	v_pk_fma_f32 v[230:231], v[42:43], v[190:191], v[230:231]
	s_and_saveexec_b64 s[52:53], s[8:9]
	ds_write_b32 v63, v246 offset:256
	s_or_b64 exec, exec, s[52:53]
	v_pk_add_f32 v[228:229], v[228:229], v[230:231]
	v_lshlrev_b32_e32 v210, 16, v192
	v_lshlrev_b32_e32 v211, 16, v193
	v_add_f32_e32 v232, v228, v229
	v_lshlrev_b32_e32 v212, 16, v194
	v_lshlrev_b32_e32 v213, 16, v195
	v_add_f32_dpp v232, v232, v232 quad_perm:[1,0,3,2] row_mask:0xf bank_mask:0xf bound_ctrl:1
	v_pk_fma_f32 v[234:235], v[40:41], v[192:193], v[40:41] neg_lo:[1,0,0] neg_hi:[1,0,0]
	v_pk_fma_f32 v[236:237], v[42:43], v[194:195], v[42:43] neg_lo:[1,0,0] neg_hi:[1,0,0]
	v_add_f32_dpp v232, v232, v232 quad_perm:[2,3,0,1] row_mask:0xf bank_mask:0xf bound_ctrl:1
	v_pk_fma_f32 v[238:239], v[44:45], v[210:211], v[44:45] neg_lo:[1,0,0] neg_hi:[1,0,0]
	v_pk_fma_f32 v[240:241], v[46:47], v[212:213], v[46:47] neg_lo:[1,0,0] neg_hi:[1,0,0]
	v_add_f32_dpp v232, v232, v232 row_half_mirror row_mask:0xf bank_mask:0xf bound_ctrl:1
	v_lshlrev_b32_e32 v226, 16, v204
	v_lshlrev_b32_e32 v214, 16, v196
	v_lshlrev_b32_e32 v215, 16, v197
	v_lshlrev_b32_e32 v216, 16, v198
	v_lshlrev_b32_e32 v217, 16, v199
	v_pk_fma_f32 v[234:235], v[226:227], v[196:197], v[234:235] op_sel_hi:[0,1,1]
	v_pk_fma_f32 v[236:237], v[226:227], v[198:199], v[236:237] op_sel_hi:[0,1,1]
	v_pk_fma_f32 v[238:239], v[226:227], v[214:215], v[238:239] op_sel_hi:[0,1,1]
	v_pk_fma_f32 v[240:241], v[226:227], v[216:217], v[240:241] op_sel_hi:[0,1,1]
	v_lshlrev_b32_e32 v218, 16, v200
	v_lshlrev_b32_e32 v219, 16, v201
	v_lshlrev_b32_e32 v220, 16, v202
	v_lshlrev_b32_e32 v221, 16, v203
	v_pk_fma_f32 v[40:41], v[232:233], v[200:201], v[234:235] op_sel_hi:[0,1,1] neg_lo:[1,0,0] neg_hi:[1,0,0]
	v_pk_fma_f32 v[42:43], v[232:233], v[202:203], v[236:237] op_sel_hi:[0,1,1] neg_lo:[1,0,0] neg_hi:[1,0,0]
	v_pk_fma_f32 v[44:45], v[232:233], v[218:219], v[238:239] op_sel_hi:[0,1,1] neg_lo:[1,0,0] neg_hi:[1,0,0]
	v_pk_fma_f32 v[46:47], v[232:233], v[220:221], v[240:241] op_sel_hi:[0,1,1] neg_lo:[1,0,0] neg_hi:[1,0,0]
	v_lshlrev_b32_e32 v222, 16, v184
	v_lshlrev_b32_e32 v223, 16, v185
	v_lshlrev_b32_e32 v224, 16, v186
	v_lshlrev_b32_e32 v225, 16, v187
	v_pk_mul_f32 v[242:243], v[40:41], v[184:185]
	v_pk_mul_f32 v[244:245], v[42:43], v[186:187]
	v_pk_fma_f32 v[242:243], v[44:45], v[222:223], v[242:243]
	v_pk_fma_f32 v[244:245], v[46:47], v[224:225], v[244:245]
	s_nop 0
	v_pk_add_f32 v[242:243], v[242:243], v[244:245]
	s_nop 0
	v_add_f32_e32 v248, v242, v243
	s_nop 1
	v_add_f32_dpp v248, v248, v248 quad_perm:[1,0,3,2] row_mask:0xf bank_mask:0xf bound_ctrl:1
	s_nop 1
	v_add_f32_dpp v248, v248, v248 quad_perm:[2,3,0,1] row_mask:0xf bank_mask:0xf bound_ctrl:1
	s_nop 1
	v_add_f32_dpp v248, v248, v248 row_half_mirror row_mask:0xf bank_mask:0xf bound_ctrl:1
	s_and_saveexec_b64 s[52:53], s[8:9]
	ds_write_b32 v63, v248 offset:384
	s_branch .LBB0_1539

.LBB0_1811:
	s_ashr_i32 s11, s10, 31
	s_lshl_b64 s[10:11], s[10:11], 12
	s_add_u32 s12, s12, s10
	s_addc_u32 s13, s13, s11
	s_ashr_i32 s19, s18, 31
	s_lshl_b64 s[10:11], s[18:19], 12
	s_add_u32 s10, s20, s10
	s_addc_u32 s11, s21, s11
	s_add_u32 s6, s8, s16
	s_addc_u32 s9, s9, s17
	s_add_u32 s8, s6, 0x17d0000
	s_addc_u32 s9, s9, 0
	s_waitcnt vmcnt(0)
	v_and_b32_e32 v66, 15, v202
	v_lshl_add_u32 v66, v66, 3, s58
	v_lshlrev_b32_e32 v164, 2, v66
	global_load_dwordx4 v[84:87], v164, s[8:9]
	global_load_dwordx4 v[88:91], v164, s[8:9] offset:16
	v_lshrrev_b32_e32 v67, 4, v202
	v_lshlrev_b32_e32 v67, 12, v67
	v_lshl_add_u32 v165, v66, 1, v67
	v_mov_b32_e32 v68, v165
	v_add_u32_e32 v69, 0x10000, v165
	v_add_u32_e32 v70, 0x40000, v165
	v_add_u32_e32 v71, 0x50000, v165
	v_add_u32_e32 v72, 0x20000, v165
	v_add_u32_e32 v73, 0x30000, v165
	v_add_u32_e32 v74, 0x60000, v165
	v_add_u32_e32 v75, 0x70000, v165
	global_load_dwordx4 v[92:95], v68, s[12:13]
	global_load_dwordx4 v[96:99], v69, s[12:13]
	global_load_dwordx4 v[100:103], v70, s[12:13]
	global_load_dwordx4 v[104:107], v71, s[12:13]
	global_load_dwordx4 v[108:111], v72, s[12:13]
	global_load_dwordx4 v[112:115], v73, s[12:13]
	global_load_dwordx4 v[116:119], v74, s[12:13]
	global_load_dwordx4 v[120:123], v75, s[12:13]
	v_lshrrev_b32_e32 v66, 7, v202
	v_bfe_u32 v67, v202, 5, 1
	v_lshlrev_b32_e32 v66, 5, v66
	v_lshl_or_b32 v66, v67, 2, v66
	v_mul_u32_u24_e32 v66, 132, v66
	v_and_b32_e32 v67, 0x5f, v202
	v_add_lshl_u32 v65, v66, v67, 2
	v_lshrrev_b32_e32 v66, 4, v202
	v_mul_u32_u24_e32 v66, 132, v66
	v_and_b32_e32 v67, 15, v202
	v_lshl_add_u32 v66, v67, 3, v66
	v_lshlrev_b32_e32 v64, 2, v66
	s_barrier
	ds_write_b32 v65, v48
	ds_write_b32 v65, v49 offset:528
	ds_write_b32 v65, v50 offset:1056
	ds_write_b32 v65, v51 offset:1584
	ds_write_b32 v65, v52 offset:4224
	ds_write_b32 v65, v53 offset:4752
	ds_write_b32 v65, v54 offset:5280
	ds_write_b32 v65, v55 offset:5808
	ds_write_b32 v65, v56 offset:8448
	ds_write_b32 v65, v57 offset:8976
	ds_write_b32 v65, v58 offset:9504
	ds_write_b32 v65, v59 offset:10032
	ds_write_b32 v65, v60 offset:12672
	ds_write_b32 v65, v61 offset:13200
	ds_write_b32 v65, v62 offset:13728
	ds_write_b32 v65, v63 offset:14256
	ds_write_b32 v65, v16 offset:128
	ds_write_b32 v65, v17 offset:656
	ds_write_b32 v65, v18 offset:1184
	ds_write_b32 v65, v19 offset:1712
	ds_write_b32 v65, v20 offset:4352
	ds_write_b32 v65, v21 offset:4880
	ds_write_b32 v65, v22 offset:5408
	ds_write_b32 v65, v23 offset:5936
	ds_write_b32 v65, v24 offset:8576
	ds_write_b32 v65, v25 offset:9104
	ds_write_b32 v65, v26 offset:9632
	ds_write_b32 v65, v27 offset:10160
	ds_write_b32 v65, v28 offset:12800
	ds_write_b32 v65, v29 offset:13328
	ds_write_b32 v65, v30 offset:13856
	ds_write_b32 v65, v31 offset:14384
	s_waitcnt lgkmcnt(0)
	s_barrier
	ds_read_b128 v[48:51], v64
	ds_read_b128 v[52:55], v64 offset:16
	ds_read_b128 v[56:59], v64 offset:8448
	ds_read_b128 v[60:63], v64 offset:8464
	ds_read_b128 v[16:19], v64 offset:16896
	ds_read_b128 v[20:23], v64 offset:16912
	ds_read_b128 v[24:27], v64 offset:25344
	ds_read_b128 v[28:31], v64 offset:25360
	s_waitcnt vmcnt(7) lgkmcnt(6)
	v_lshlrev_b32_e32 v167, 16, v92
	v_and_b32_e32 v168, 0xffff0000, v92
	v_fma_f32 v48, v48, v84, v167
	v_fma_f32 v49, v49, v85, v168
	v_lshlrev_b32_e32 v167, 16, v93
	v_and_b32_e32 v168, 0xffff0000, v93
	v_fma_f32 v50, v50, v86, v167
	v_fma_f32 v51, v51, v87, v168
	v_lshlrev_b32_e32 v167, 16, v94
	v_and_b32_e32 v168, 0xffff0000, v94
	v_fma_f32 v52, v52, v88, v167
	v_fma_f32 v53, v53, v89, v168
	v_lshlrev_b32_e32 v167, 16, v95
	v_and_b32_e32 v168, 0xffff0000, v95
	v_fma_f32 v54, v54, v90, v167
	v_fma_f32 v55, v55, v91, v168
	v_cvt_pk_bf16_f32 v48, v48, v49
	v_cvt_pk_bf16_f32 v49, v50, v51
	v_cvt_pk_bf16_f32 v50, v52, v53
	v_cvt_pk_bf16_f32 v51, v54, v55
	global_store_dwordx4 v68, v[48:51], s[10:11]
	s_waitcnt vmcnt(7) lgkmcnt(4)
	v_lshlrev_b32_e32 v167, 16, v96
	v_and_b32_e32 v168, 0xffff0000, v96
	v_fma_f32 v56, v56, v84, v167
	v_fma_f32 v57, v57, v85, v168
	v_lshlrev_b32_e32 v167, 16, v97
	v_and_b32_e32 v168, 0xffff0000, v97
	v_fma_f32 v58, v58, v86, v167
	v_fma_f32 v59, v59, v87, v168
	v_lshlrev_b32_e32 v167, 16, v98
	v_and_b32_e32 v168, 0xffff0000, v98
	v_fma_f32 v60, v60, v88, v167
	v_fma_f32 v61, v61, v89, v168
	v_lshlrev_b32_e32 v167, 16, v99
	v_and_b32_e32 v168, 0xffff0000, v99
	v_fma_f32 v62, v62, v90, v167
	v_fma_f32 v63, v63, v91, v168
	v_cvt_pk_bf16_f32 v56, v56, v57
	v_cvt_pk_bf16_f32 v57, v58, v59
	v_cvt_pk_bf16_f32 v58, v60, v61
	v_cvt_pk_bf16_f32 v59, v62, v63
	global_store_dwordx4 v69, v[56:59], s[10:11]
	s_waitcnt vmcnt(7) lgkmcnt(2)
	v_lshlrev_b32_e32 v167, 16, v100
	v_and_b32_e32 v168, 0xffff0000, v100
	v_fma_f32 v16, v16, v84, v167
	v_fma_f32 v17, v17, v85, v168
	v_lshlrev_b32_e32 v167, 16, v101
	v_and_b32_e32 v168, 0xffff0000, v101
	v_fma_f32 v18, v18, v86, v167
	v_fma_f32 v19, v19, v87, v168
	v_lshlrev_b32_e32 v167, 16, v102
	v_and_b32_e32 v168, 0xffff0000, v102
	v_fma_f32 v20, v20, v88, v167
	v_fma_f32 v21, v21, v89, v168
	v_lshlrev_b32_e32 v167, 16, v103
	v_and_b32_e32 v168, 0xffff0000, v103
	v_fma_f32 v22, v22, v90, v167
	v_fma_f32 v23, v23, v91, v168
	v_cvt_pk_bf16_f32 v16, v16, v17
	v_cvt_pk_bf16_f32 v17, v18, v19
	v_cvt_pk_bf16_f32 v18, v20, v21
	v_cvt_pk_bf16_f32 v19, v22, v23
	global_store_dwordx4 v70, v[16:19], s[10:11]
	s_waitcnt vmcnt(7) lgkmcnt(0)
	v_lshlrev_b32_e32 v167, 16, v104
	v_and_b32_e32 v168, 0xffff0000, v104
	v_fma_f32 v24, v24, v84, v167
	v_fma_f32 v25, v25, v85, v168
	v_lshlrev_b32_e32 v167, 16, v105
	v_and_b32_e32 v168, 0xffff0000, v105
	v_fma_f32 v26, v26, v86, v167
	v_fma_f32 v27, v27, v87, v168
	v_lshlrev_b32_e32 v167, 16, v106
	v_and_b32_e32 v168, 0xffff0000, v106
	v_fma_f32 v28, v28, v88, v167
	v_fma_f32 v29, v29, v89, v168
	v_lshlrev_b32_e32 v167, 16, v107
	v_and_b32_e32 v168, 0xffff0000, v107
	v_fma_f32 v30, v30, v90, v167
	v_fma_f32 v31, v31, v91, v168
	v_cvt_pk_bf16_f32 v24, v24, v25
	v_cvt_pk_bf16_f32 v25, v26, v27
	v_cvt_pk_bf16_f32 v26, v28, v29
	v_cvt_pk_bf16_f32 v27, v30, v31
	global_store_dwordx4 v71, v[24:27], s[10:11]
	s_barrier
	ds_write_b32 v65, v32
	ds_write_b32 v65, v33 offset:528
	ds_write_b32 v65, v34 offset:1056
	ds_write_b32 v65, v35 offset:1584
	ds_write_b32 v65, v36 offset:4224
	ds_write_b32 v65, v37 offset:4752
	ds_write_b32 v65, v38 offset:5280
	ds_write_b32 v65, v39 offset:5808
	ds_write_b32 v65, v40 offset:8448
	ds_write_b32 v65, v41 offset:8976
	ds_write_b32 v65, v42 offset:9504
	ds_write_b32 v65, v43 offset:10032
	ds_write_b32 v65, v44 offset:12672
	ds_write_b32 v65, v45 offset:13200
	ds_write_b32 v65, v46 offset:13728
	ds_write_b32 v65, v47 offset:14256
	ds_write_b32 v65, v0 offset:128
	ds_write_b32 v65, v1 offset:656
	ds_write_b32 v65, v2 offset:1184
	ds_write_b32 v65, v3 offset:1712
	ds_write_b32 v65, v4 offset:4352
	ds_write_b32 v65, v5 offset:4880
	ds_write_b32 v65, v6 offset:5408
	ds_write_b32 v65, v7 offset:5936
	ds_write_b32 v65, v8 offset:8576
	ds_write_b32 v65, v9 offset:9104
	ds_write_b32 v65, v10 offset:9632
	ds_write_b32 v65, v11 offset:10160
	ds_write_b32 v65, v12 offset:12800
	ds_write_b32 v65, v13 offset:13328
	ds_write_b32 v65, v14 offset:13856
	ds_write_b32 v65, v15 offset:14384
	s_waitcnt lgkmcnt(0)
	s_barrier
	ds_read_b128 v[32:35], v64
	ds_read_b128 v[36:39], v64 offset:16
	ds_read_b128 v[40:43], v64 offset:8448
	ds_read_b128 v[44:47], v64 offset:8464
	ds_read_b128 v[0:3], v64 offset:16896
	ds_read_b128 v[4:7], v64 offset:16912
	ds_read_b128 v[8:11], v64 offset:25344
	ds_read_b128 v[12:15], v64 offset:25360
	s_waitcnt vmcnt(7) lgkmcnt(6)
	v_lshlrev_b32_e32 v167, 16, v108
	v_and_b32_e32 v168, 0xffff0000, v108
	v_fma_f32 v32, v32, v84, v167
	v_fma_f32 v33, v33, v85, v168
	v_lshlrev_b32_e32 v167, 16, v109
	v_and_b32_e32 v168, 0xffff0000, v109
	v_fma_f32 v34, v34, v86, v167
	v_fma_f32 v35, v35, v87, v168
	v_lshlrev_b32_e32 v167, 16, v110
	v_and_b32_e32 v168, 0xffff0000, v110
	v_fma_f32 v36, v36, v88, v167
	v_fma_f32 v37, v37, v89, v168
	v_lshlrev_b32_e32 v167, 16, v111
	v_and_b32_e32 v168, 0xffff0000, v111
	v_fma_f32 v38, v38, v90, v167
	v_fma_f32 v39, v39, v91, v168
	v_cvt_pk_bf16_f32 v32, v32, v33
	v_cvt_pk_bf16_f32 v33, v34, v35
	v_cvt_pk_bf16_f32 v34, v36, v37
	v_cvt_pk_bf16_f32 v35, v38, v39
	global_store_dwordx4 v72, v[32:35], s[10:11]
	s_waitcnt vmcnt(7) lgkmcnt(4)
	v_lshlrev_b32_e32 v167, 16, v112
	v_and_b32_e32 v168, 0xffff0000, v112
	v_fma_f32 v40, v40, v84, v167
	v_fma_f32 v41, v41, v85, v168
	v_lshlrev_b32_e32 v167, 16, v113
	v_and_b32_e32 v168, 0xffff0000, v113
	v_fma_f32 v42, v42, v86, v167
	v_fma_f32 v43, v43, v87, v168
	v_lshlrev_b32_e32 v167, 16, v114
	v_and_b32_e32 v168, 0xffff0000, v114
	v_fma_f32 v44, v44, v88, v167
	v_fma_f32 v45, v45, v89, v168
	v_lshlrev_b32_e32 v167, 16, v115
	v_and_b32_e32 v168, 0xffff0000, v115
	v_fma_f32 v46, v46, v90, v167
	v_fma_f32 v47, v47, v91, v168
	v_cvt_pk_bf16_f32 v40, v40, v41
	v_cvt_pk_bf16_f32 v41, v42, v43
	v_cvt_pk_bf16_f32 v42, v44, v45
	v_cvt_pk_bf16_f32 v43, v46, v47
	global_store_dwordx4 v73, v[40:43], s[10:11]
	s_waitcnt vmcnt(7) lgkmcnt(2)
	v_lshlrev_b32_e32 v167, 16, v116
	v_and_b32_e32 v168, 0xffff0000, v116
	v_fma_f32 v0, v0, v84, v167
	v_fma_f32 v1, v1, v85, v168
	v_lshlrev_b32_e32 v167, 16, v117
	v_and_b32_e32 v168, 0xffff0000, v117
	v_fma_f32 v2, v2, v86, v167
	v_fma_f32 v3, v3, v87, v168
	v_lshlrev_b32_e32 v167, 16, v118
	v_and_b32_e32 v168, 0xffff0000, v118
	v_fma_f32 v4, v4, v88, v167
	v_fma_f32 v5, v5, v89, v168
	v_lshlrev_b32_e32 v167, 16, v119
	v_and_b32_e32 v168, 0xffff0000, v119
	v_fma_f32 v6, v6, v90, v167
	v_fma_f32 v7, v7, v91, v168
	v_cvt_pk_bf16_f32 v0, v0, v1
	v_cvt_pk_bf16_f32 v1, v2, v3
	v_cvt_pk_bf16_f32 v2, v4, v5
	v_cvt_pk_bf16_f32 v3, v6, v7
	global_store_dwordx4 v74, v[0:3], s[10:11]
	s_waitcnt vmcnt(7) lgkmcnt(0)
	v_lshlrev_b32_e32 v167, 16, v120
	v_and_b32_e32 v168, 0xffff0000, v120
	v_fma_f32 v8, v8, v84, v167
	v_fma_f32 v9, v9, v85, v168
	v_lshlrev_b32_e32 v167, 16, v121
	v_and_b32_e32 v168, 0xffff0000, v121
	v_fma_f32 v10, v10, v86, v167
	v_fma_f32 v11, v11, v87, v168
	v_lshlrev_b32_e32 v167, 16, v122
	v_and_b32_e32 v168, 0xffff0000, v122
	v_fma_f32 v12, v12, v88, v167
	v_fma_f32 v13, v13, v89, v168
	v_lshlrev_b32_e32 v167, 16, v123
	v_and_b32_e32 v168, 0xffff0000, v123
	v_fma_f32 v14, v14, v90, v167
	v_fma_f32 v15, v15, v91, v168
	v_cvt_pk_bf16_f32 v8, v8, v9
	v_cvt_pk_bf16_f32 v9, v10, v11
	v_cvt_pk_bf16_f32 v10, v12, v13
	v_cvt_pk_bf16_f32 v11, v14, v15
	global_store_dwordx4 v75, v[8:11], s[10:11]
	s_add_i32 s57, s57, s26
	s_add_i32 s56, s56, s34
	s_cmpk_gt_u32 s57, 0xff
	s_cbranch_scc1 .LBB0_1805

.LBB0_2044:
	s_ashr_i32 s11, s10, 31
	s_lshl_b64 s[10:11], s[10:11], 12
	s_add_u32 s12, s12, s10
	s_addc_u32 s13, s13, s11
	s_ashr_i32 s17, s16, 31
	s_lshl_b64 s[10:11], s[16:17], 12
	s_add_u32 s10, s18, s10
	s_addc_u32 s11, s19, s11
	s_add_u32 s0, s8, s14
	s_addc_u32 s9, s9, s15
	s_add_u32 s8, s0, 0x17d3000
	s_addc_u32 s9, s9, 0
	s_waitcnt vmcnt(0)
	v_and_b32_e32 v66, 15, v202
	v_lshl_add_u32 v66, v66, 3, s59
	v_lshlrev_b32_e32 v164, 2, v66
	global_load_dwordx4 v[84:87], v164, s[8:9]
	global_load_dwordx4 v[88:91], v164, s[8:9] offset:16
	v_lshrrev_b32_e32 v67, 4, v202
	v_lshlrev_b32_e32 v67, 12, v67
	v_lshl_add_u32 v165, v66, 1, v67
	v_mov_b32_e32 v68, v165
	v_add_u32_e32 v69, 0x10000, v165
	v_add_u32_e32 v70, 0x40000, v165
	v_add_u32_e32 v71, 0x50000, v165
	v_add_u32_e32 v72, 0x20000, v165
	v_add_u32_e32 v73, 0x30000, v165
	v_add_u32_e32 v74, 0x60000, v165
	v_add_u32_e32 v75, 0x70000, v165
	global_load_dwordx4 v[92:95], v68, s[12:13]
	global_load_dwordx4 v[96:99], v69, s[12:13]
	global_load_dwordx4 v[100:103], v70, s[12:13]
	global_load_dwordx4 v[104:107], v71, s[12:13]
	global_load_dwordx4 v[108:111], v72, s[12:13]
	global_load_dwordx4 v[112:115], v73, s[12:13]
	global_load_dwordx4 v[116:119], v74, s[12:13]
	global_load_dwordx4 v[120:123], v75, s[12:13]
	v_lshrrev_b32_e32 v66, 7, v202
	v_bfe_u32 v67, v202, 5, 1
	v_lshlrev_b32_e32 v66, 5, v66
	v_lshl_or_b32 v66, v67, 2, v66
	v_mul_u32_u24_e32 v66, 132, v66
	v_and_b32_e32 v67, 0x5f, v202
	v_add_lshl_u32 v65, v66, v67, 2
	v_lshrrev_b32_e32 v66, 4, v202
	v_mul_u32_u24_e32 v66, 132, v66
	v_and_b32_e32 v67, 15, v202
	v_lshl_add_u32 v66, v67, 3, v66
	v_lshlrev_b32_e32 v64, 2, v66
	s_barrier
	ds_write_b32 v65, v48
	ds_write_b32 v65, v49 offset:528
	ds_write_b32 v65, v50 offset:1056
	ds_write_b32 v65, v51 offset:1584
	ds_write_b32 v65, v52 offset:4224
	ds_write_b32 v65, v53 offset:4752
	ds_write_b32 v65, v54 offset:5280
	ds_write_b32 v65, v55 offset:5808
	ds_write_b32 v65, v56 offset:8448
	ds_write_b32 v65, v57 offset:8976
	ds_write_b32 v65, v58 offset:9504
	ds_write_b32 v65, v59 offset:10032
	ds_write_b32 v65, v60 offset:12672
	ds_write_b32 v65, v61 offset:13200
	ds_write_b32 v65, v62 offset:13728
	ds_write_b32 v65, v63 offset:14256
	ds_write_b32 v65, v16 offset:128
	ds_write_b32 v65, v17 offset:656
	ds_write_b32 v65, v18 offset:1184
	ds_write_b32 v65, v19 offset:1712
	ds_write_b32 v65, v20 offset:4352
	ds_write_b32 v65, v21 offset:4880
	ds_write_b32 v65, v22 offset:5408
	ds_write_b32 v65, v23 offset:5936
	ds_write_b32 v65, v24 offset:8576
	ds_write_b32 v65, v25 offset:9104
	ds_write_b32 v65, v26 offset:9632
	ds_write_b32 v65, v27 offset:10160
	ds_write_b32 v65, v28 offset:12800
	ds_write_b32 v65, v29 offset:13328
	ds_write_b32 v65, v30 offset:13856
	ds_write_b32 v65, v31 offset:14384
	s_waitcnt lgkmcnt(0)
	s_barrier
	ds_read_b128 v[48:51], v64
	ds_read_b128 v[52:55], v64 offset:16
	ds_read_b128 v[56:59], v64 offset:8448
	ds_read_b128 v[60:63], v64 offset:8464
	ds_read_b128 v[16:19], v64 offset:16896
	ds_read_b128 v[20:23], v64 offset:16912
	ds_read_b128 v[24:27], v64 offset:25344
	ds_read_b128 v[28:31], v64 offset:25360
	s_waitcnt vmcnt(7) lgkmcnt(6)
	v_lshlrev_b32_e32 v167, 16, v92
	v_and_b32_e32 v168, 0xffff0000, v92
	v_fma_f32 v48, v48, v84, v167
	v_fma_f32 v49, v49, v85, v168
	v_lshlrev_b32_e32 v167, 16, v93
	v_and_b32_e32 v168, 0xffff0000, v93
	v_fma_f32 v50, v50, v86, v167
	v_fma_f32 v51, v51, v87, v168
	v_lshlrev_b32_e32 v167, 16, v94
	v_and_b32_e32 v168, 0xffff0000, v94
	v_fma_f32 v52, v52, v88, v167
	v_fma_f32 v53, v53, v89, v168
	v_lshlrev_b32_e32 v167, 16, v95
	v_and_b32_e32 v168, 0xffff0000, v95
	v_fma_f32 v54, v54, v90, v167
	v_fma_f32 v55, v55, v91, v168
	v_cvt_pk_bf16_f32 v48, v48, v49
	v_cvt_pk_bf16_f32 v49, v50, v51
	v_cvt_pk_bf16_f32 v50, v52, v53
	v_cvt_pk_bf16_f32 v51, v54, v55
	global_store_dwordx4 v68, v[48:51], s[10:11]
	s_waitcnt vmcnt(7) lgkmcnt(4)
	v_lshlrev_b32_e32 v167, 16, v96
	v_and_b32_e32 v168, 0xffff0000, v96
	v_fma_f32 v56, v56, v84, v167
	v_fma_f32 v57, v57, v85, v168
	v_lshlrev_b32_e32 v167, 16, v97
	v_and_b32_e32 v168, 0xffff0000, v97
	v_fma_f32 v58, v58, v86, v167
	v_fma_f32 v59, v59, v87, v168
	v_lshlrev_b32_e32 v167, 16, v98
	v_and_b32_e32 v168, 0xffff0000, v98
	v_fma_f32 v60, v60, v88, v167
	v_fma_f32 v61, v61, v89, v168
	v_lshlrev_b32_e32 v167, 16, v99
	v_and_b32_e32 v168, 0xffff0000, v99
	v_fma_f32 v62, v62, v90, v167
	v_fma_f32 v63, v63, v91, v168
	v_cvt_pk_bf16_f32 v56, v56, v57
	v_cvt_pk_bf16_f32 v57, v58, v59
	v_cvt_pk_bf16_f32 v58, v60, v61
	v_cvt_pk_bf16_f32 v59, v62, v63
	global_store_dwordx4 v69, v[56:59], s[10:11]
	s_waitcnt vmcnt(7) lgkmcnt(2)
	v_lshlrev_b32_e32 v167, 16, v100
	v_and_b32_e32 v168, 0xffff0000, v100
	v_fma_f32 v16, v16, v84, v167
	v_fma_f32 v17, v17, v85, v168
	v_lshlrev_b32_e32 v167, 16, v101
	v_and_b32_e32 v168, 0xffff0000, v101
	v_fma_f32 v18, v18, v86, v167
	v_fma_f32 v19, v19, v87, v168
	v_lshlrev_b32_e32 v167, 16, v102
	v_and_b32_e32 v168, 0xffff0000, v102
	v_fma_f32 v20, v20, v88, v167
	v_fma_f32 v21, v21, v89, v168
	v_lshlrev_b32_e32 v167, 16, v103
	v_and_b32_e32 v168, 0xffff0000, v103
	v_fma_f32 v22, v22, v90, v167
	v_fma_f32 v23, v23, v91, v168
	v_cvt_pk_bf16_f32 v16, v16, v17
	v_cvt_pk_bf16_f32 v17, v18, v19
	v_cvt_pk_bf16_f32 v18, v20, v21
	v_cvt_pk_bf16_f32 v19, v22, v23
	global_store_dwordx4 v70, v[16:19], s[10:11]
	s_waitcnt vmcnt(7) lgkmcnt(0)
	v_lshlrev_b32_e32 v167, 16, v104
	v_and_b32_e32 v168, 0xffff0000, v104
	v_fma_f32 v24, v24, v84, v167
	v_fma_f32 v25, v25, v85, v168
	v_lshlrev_b32_e32 v167, 16, v105
	v_and_b32_e32 v168, 0xffff0000, v105
	v_fma_f32 v26, v26, v86, v167
	v_fma_f32 v27, v27, v87, v168
	v_lshlrev_b32_e32 v167, 16, v106
	v_and_b32_e32 v168, 0xffff0000, v106
	v_fma_f32 v28, v28, v88, v167
	v_fma_f32 v29, v29, v89, v168
	v_lshlrev_b32_e32 v167, 16, v107
	v_and_b32_e32 v168, 0xffff0000, v107
	v_fma_f32 v30, v30, v90, v167
	v_fma_f32 v31, v31, v91, v168
	v_cvt_pk_bf16_f32 v24, v24, v25
	v_cvt_pk_bf16_f32 v25, v26, v27
	v_cvt_pk_bf16_f32 v26, v28, v29
	v_cvt_pk_bf16_f32 v27, v30, v31
	global_store_dwordx4 v71, v[24:27], s[10:11]
	s_barrier
	ds_write_b32 v65, v32
	ds_write_b32 v65, v33 offset:528
	ds_write_b32 v65, v34 offset:1056
	ds_write_b32 v65, v35 offset:1584
	ds_write_b32 v65, v36 offset:4224
	ds_write_b32 v65, v37 offset:4752
	ds_write_b32 v65, v38 offset:5280
	ds_write_b32 v65, v39 offset:5808
	ds_write_b32 v65, v40 offset:8448
	ds_write_b32 v65, v41 offset:8976
	ds_write_b32 v65, v42 offset:9504
	ds_write_b32 v65, v43 offset:10032
	ds_write_b32 v65, v44 offset:12672
	ds_write_b32 v65, v45 offset:13200
	ds_write_b32 v65, v46 offset:13728
	ds_write_b32 v65, v47 offset:14256
	ds_write_b32 v65, v0 offset:128
	ds_write_b32 v65, v1 offset:656
	ds_write_b32 v65, v2 offset:1184
	ds_write_b32 v65, v3 offset:1712
	ds_write_b32 v65, v4 offset:4352
	ds_write_b32 v65, v5 offset:4880
	ds_write_b32 v65, v6 offset:5408
	ds_write_b32 v65, v7 offset:5936
	ds_write_b32 v65, v8 offset:8576
	ds_write_b32 v65, v9 offset:9104
	ds_write_b32 v65, v10 offset:9632
	ds_write_b32 v65, v11 offset:10160
	ds_write_b32 v65, v12 offset:12800
	ds_write_b32 v65, v13 offset:13328
	ds_write_b32 v65, v14 offset:13856
	ds_write_b32 v65, v15 offset:14384
	s_waitcnt lgkmcnt(0)
	s_barrier
	ds_read_b128 v[32:35], v64
	ds_read_b128 v[36:39], v64 offset:16
	ds_read_b128 v[40:43], v64 offset:8448
	ds_read_b128 v[44:47], v64 offset:8464
	ds_read_b128 v[0:3], v64 offset:16896
	ds_read_b128 v[4:7], v64 offset:16912
	ds_read_b128 v[8:11], v64 offset:25344
	ds_read_b128 v[12:15], v64 offset:25360
	s_waitcnt vmcnt(7) lgkmcnt(6)
	v_lshlrev_b32_e32 v167, 16, v108
	v_and_b32_e32 v168, 0xffff0000, v108
	v_fma_f32 v32, v32, v84, v167
	v_fma_f32 v33, v33, v85, v168
	v_lshlrev_b32_e32 v167, 16, v109
	v_and_b32_e32 v168, 0xffff0000, v109
	v_fma_f32 v34, v34, v86, v167
	v_fma_f32 v35, v35, v87, v168
	v_lshlrev_b32_e32 v167, 16, v110
	v_and_b32_e32 v168, 0xffff0000, v110
	v_fma_f32 v36, v36, v88, v167
	v_fma_f32 v37, v37, v89, v168
	v_lshlrev_b32_e32 v167, 16, v111
	v_and_b32_e32 v168, 0xffff0000, v111
	v_fma_f32 v38, v38, v90, v167
	v_fma_f32 v39, v39, v91, v168
	v_cvt_pk_bf16_f32 v32, v32, v33
	v_cvt_pk_bf16_f32 v33, v34, v35
	v_cvt_pk_bf16_f32 v34, v36, v37
	v_cvt_pk_bf16_f32 v35, v38, v39
	global_store_dwordx4 v72, v[32:35], s[10:11]
	s_waitcnt vmcnt(7) lgkmcnt(4)
	v_lshlrev_b32_e32 v167, 16, v112
	v_and_b32_e32 v168, 0xffff0000, v112
	v_fma_f32 v40, v40, v84, v167
	v_fma_f32 v41, v41, v85, v168
	v_lshlrev_b32_e32 v167, 16, v113
	v_and_b32_e32 v168, 0xffff0000, v113
	v_fma_f32 v42, v42, v86, v167
	v_fma_f32 v43, v43, v87, v168
	v_lshlrev_b32_e32 v167, 16, v114
	v_and_b32_e32 v168, 0xffff0000, v114
	v_fma_f32 v44, v44, v88, v167
	v_fma_f32 v45, v45, v89, v168
	v_lshlrev_b32_e32 v167, 16, v115
	v_and_b32_e32 v168, 0xffff0000, v115
	v_fma_f32 v46, v46, v90, v167
	v_fma_f32 v47, v47, v91, v168
	v_cvt_pk_bf16_f32 v40, v40, v41
	v_cvt_pk_bf16_f32 v41, v42, v43
	v_cvt_pk_bf16_f32 v42, v44, v45
	v_cvt_pk_bf16_f32 v43, v46, v47
	global_store_dwordx4 v73, v[40:43], s[10:11]
	s_waitcnt vmcnt(7) lgkmcnt(2)
	v_lshlrev_b32_e32 v167, 16, v116
	v_and_b32_e32 v168, 0xffff0000, v116
	v_fma_f32 v0, v0, v84, v167
	v_fma_f32 v1, v1, v85, v168
	v_lshlrev_b32_e32 v167, 16, v117
	v_and_b32_e32 v168, 0xffff0000, v117
	v_fma_f32 v2, v2, v86, v167
	v_fma_f32 v3, v3, v87, v168
	v_lshlrev_b32_e32 v167, 16, v118
	v_and_b32_e32 v168, 0xffff0000, v118
	v_fma_f32 v4, v4, v88, v167
	v_fma_f32 v5, v5, v89, v168
	v_lshlrev_b32_e32 v167, 16, v119
	v_and_b32_e32 v168, 0xffff0000, v119
	v_fma_f32 v6, v6, v90, v167
	v_fma_f32 v7, v7, v91, v168
	v_cvt_pk_bf16_f32 v0, v0, v1
	v_cvt_pk_bf16_f32 v1, v2, v3
	v_cvt_pk_bf16_f32 v2, v4, v5
	v_cvt_pk_bf16_f32 v3, v6, v7
	global_store_dwordx4 v74, v[0:3], s[10:11]
	s_waitcnt vmcnt(7) lgkmcnt(0)
	v_lshlrev_b32_e32 v167, 16, v120
	v_and_b32_e32 v168, 0xffff0000, v120
	v_fma_f32 v8, v8, v84, v167
	v_fma_f32 v9, v9, v85, v168
	v_lshlrev_b32_e32 v167, 16, v121
	v_and_b32_e32 v168, 0xffff0000, v121
	v_fma_f32 v10, v10, v86, v167
	v_fma_f32 v11, v11, v87, v168
	v_lshlrev_b32_e32 v167, 16, v122
	v_and_b32_e32 v168, 0xffff0000, v122
	v_fma_f32 v12, v12, v88, v167
	v_fma_f32 v13, v13, v89, v168
	v_lshlrev_b32_e32 v167, 16, v123
	v_and_b32_e32 v168, 0xffff0000, v123
	v_fma_f32 v14, v14, v90, v167
	v_fma_f32 v15, v15, v91, v168
	v_cvt_pk_bf16_f32 v8, v8, v9
	v_cvt_pk_bf16_f32 v9, v10, v11
	v_cvt_pk_bf16_f32 v10, v12, v13
	v_cvt_pk_bf16_f32 v11, v14, v15
	global_store_dwordx4 v75, v[8:11], s[10:11]
	s_add_i32 s58, s58, s26
	s_add_i32 s57, s57, s34
	s_cmpk_gt_u32 s58, 0xff
	s_cbranch_scc1 .LBB0_2038
